# scan x-fragment and LDS-DMA tile loads take the nt hint (keep the y tiles cache-resident for gate_norm)
# baseline (speedup 1.0000x reference)
; __device__ __forceinline__ int fresh_lane() { int l; asm volatile("v_mbcnt_lo_u32_b32 %0, -1, 0\n\tv_mbcnt_hi_u32_b32 %0, -1, %0" : "=v"(l)); return l; }
;     __device__ __forceinline__ const char* b(const pg8::Unit& u) const { return (const char*)ws + boff + (size_t)u.pn * 256 * K_ * 2 + (u.kq < 0 ? 0 : u.kq * (K_ / 4) * 2); }
;     __device__ __forceinline__ const char* b(const pg8::Unit& u) const { return (const char*)ws + boff + (size_t)u.pn * 256 * D * 2; }
;     __device__ __forceinline__ const char* b(const pg8::Unit& u) const { return (const char*)ws + boff + (size_t)u.pn * 256 * D * 2; }
;     __device__ __forceinline__ const char* b(const pg8::Unit& u) const { return (const char*)ws + WS_A + ((size_t)u.pn * 256 * D + (size_t)(u.pm >> 1) * 256) * 2; }
; #define SCAN_DMA(dstbase, srcptr_row0, pitch_elems) do { _Pragma("unroll") for (int q_ = 0; q_ < 4; ++q_) { const int idx_ = tid + 512 * q_, row_ = idx_ >> 4, c16_ = (idx_ & 15) ^ (row_ & 15); \
;         __builtin_amdgcn_global_load_lds((const unsigned*)((srcptr_row0) + (size_t)row_ * (pitch_elems) + c16_ * 8), (LAS unsigned*)((dstbase) + (w * 64 + 512 * q_) * 16), 16, 0, 0); } } while (0)
; template <int MODE> __device__ __forceinline__ void ssd_scan_phase(Frame& F, int j, bool ctx_out) {
;     ...
;         {
;             const int tid0 = w * 64 + fresh_lane(); const int tid = tid0;
;             const bool isctx0 = true; const int cc0 = dir == 0 ? 0 : 1; const int row00 = MLAT + b * LCTX + cc0 * 128;
;             if (ctx_out && !(MODE & 8) && isctx0) { SCAN_DMA(CS, cm + (size_t)row00 * GNW + g * 128, GNW); SCAN_DMA(R0, bm + (size_t)row00 * GNW + g * 128, GNW); }
;         }
.LBB0_475:
	s_ashr_i32 s10, s101, 5
	s_lshl_b32 s80, s10, 8
	v_readlane_b32 s26, v255, 33
	s_addk_i32 s80, 0x4000
	s_lshl_b32 s14, s7, 7
	v_readlane_b32 s27, v255, 34
	s_or_b32 s40, s80, s14
	s_mov_b64 s[4:5], -1
	s_and_b64 vcc, exec, s[26:27]
	v_mbcnt_lo_u32_b32 v0, -1, 0
	v_mbcnt_hi_u32_b32 v0, -1, v0
	s_cbranch_vccz .LBB0_477
	s_ashr_i32 s41, s40, 31
	s_lshl_b64 s[4:5], s[40:41], 11
	v_readlane_b32 s17, v253, 11
	v_add_u32_e32 v14, s33, v0
	s_add_u32 s17, s17, s4
	v_readlane_b32 s26, v253, 12
	s_addc_u32 s26, s26, s5
	s_lshl_b32 s42, s15, 7
	s_lshl_b32 s27, s15, 8
	v_ashrrev_i32_e32 v2, 4, v14
	s_add_u32 s30, s17, s27
	v_xor_b32_e32 v6, v2, v0
	v_ashrrev_i32_e32 v3, 31, v2
	s_addc_u32 s31, s26, 0
	v_lshlrev_b64 v[2:3], 11, v[2:3]
	v_lshlrev_b32_e32 v6, 4, v6
	v_lshl_add_u64 v[4:5], s[30:31], 0, v[2:3]
	v_and_b32_e32 v176, 0xf0, v6
	s_mov_b32 m0, s16
	v_lshl_add_u64 v[4:5], v[4:5], 0, v[176:177]
	global_load_lds_dwordx4 v[4:5], off nt
	v_add_u32_e32 v4, 0x200, v14
	v_ashrrev_i32_e32 v4, 4, v4
	v_xor_b32_e32 v8, v4, v0
	v_ashrrev_i32_e32 v5, 31, v4
	v_lshlrev_b64 v[4:5], 11, v[4:5]
	v_lshlrev_b32_e32 v8, 4, v8
	v_lshl_add_u64 v[6:7], s[30:31], 0, v[4:5]
	v_and_b32_e32 v8, 0xf0, v8
	v_mov_b32_e32 v9, v177
	v_lshl_add_u64 v[6:7], v[6:7], 0, v[8:9]
	s_add_i32 m0, s16, 0x2000
	v_mov_b32_e32 v13, v177
	global_load_lds_dwordx4 v[6:7], off nt
	v_add_u32_e32 v6, 0x400, v14
	v_ashrrev_i32_e32 v6, 4, v6
	v_xor_b32_e32 v12, v6, v0
	v_ashrrev_i32_e32 v7, 31, v6
	v_lshlrev_b64 v[6:7], 11, v[6:7]
	v_lshlrev_b32_e32 v12, 4, v12
	v_lshl_add_u64 v[10:11], s[30:31], 0, v[6:7]
	v_and_b32_e32 v12, 0xf0, v12
	v_lshl_add_u64 v[10:11], v[10:11], 0, v[12:13]
	s_add_i32 m0, s16, 0x4000
	v_mov_b32_e32 v17, v177
	global_load_lds_dwordx4 v[10:11], off nt
	v_add_u32_e32 v10, 0x600, v14
	v_ashrrev_i32_e32 v10, 4, v10
	v_ashrrev_i32_e32 v11, 31, v10
	v_xor_b32_e32 v0, v10, v0
	v_lshlrev_b64 v[10:11], 11, v[10:11]
	v_lshl_add_u64 v[14:15], s[30:31], 0, v[10:11]
	s_add_i32 m0, s16, 0x6000
	v_readlane_b32 s30, v253, 7
	v_readlane_b32 s31, v253, 8
	s_add_u32 s4, s30, s4
	s_addc_u32 s5, s31, s5
	v_lshlrev_b32_e32 v0, 4, v0
	s_add_u32 s4, s4, s27
	v_and_b32_e32 v16, 0xf0, v0
	s_addc_u32 s5, s5, 0
	v_lshl_add_u64 v[14:15], v[14:15], 0, v[16:17]
	v_lshl_add_u64 v[2:3], s[4:5], 0, v[2:3]
	global_load_lds_dwordx4 v[14:15], off nt
	v_lshl_add_u64 v[2:3], v[2:3], 0, v[176:177]
	s_add_i32 m0, s16, 0x8000
	s_mov_b32 s43, s92
	global_load_lds_dwordx4 v[2:3], off nt
	v_lshl_add_u64 v[2:3], s[4:5], 0, v[4:5]
	v_lshl_add_u64 v[2:3], v[2:3], 0, v[8:9]
	s_add_i32 m0, s16, 0xa000
	s_nop 0
	global_load_lds_dwordx4 v[2:3], off nt
	v_lshl_add_u64 v[2:3], s[4:5], 0, v[6:7]
	v_lshl_add_u64 v[2:3], v[2:3], 0, v[12:13]
	s_add_i32 m0, s16, 0xc000
	s_nop 0
	global_load_lds_dwordx4 v[2:3], off nt
	v_lshl_add_u64 v[2:3], s[4:5], 0, v[10:11]
	v_lshl_add_u64 v[2:3], v[2:3], 0, v[16:17]
	s_add_i32 m0, s16, 0xe000
	s_mov_b64 s[4:5], 0
	global_load_lds_dwordx4 v[2:3], off nt

; __device__ __forceinline__ int fresh_lane() { int l; asm volatile("v_mbcnt_lo_u32_b32 %0, -1, 0\n\tv_mbcnt_hi_u32_b32 %0, -1, %0" : "=v"(l)); return l; }
;     __device__ __forceinline__ const char* b(const pg8::Unit& u) const { return (const char*)ws + boff + (size_t)u.pn * 256 * K_ * 2 + (u.kq < 0 ? 0 : u.kq * (K_ / 4) * 2); }
;     __device__ __forceinline__ const char* b(const pg8::Unit& u) const { return (const char*)ws + boff + (size_t)u.pn * 256 * D * 2; }
;     __device__ __forceinline__ const char* b(const pg8::Unit& u) const { return (const char*)ws + boff + (size_t)u.pn * 256 * D * 2; }
; template <int MODE> __device__ __forceinline__ void ssd_scan_phase(Frame& F, int j, bool ctx_out) {
;     ...
;         const float a_h = -expf(F.in[I_ALOG][(j * 2 + dir) * NH + h]) * LOG2E;
;         const float dtbias = F.in[I_DTB][(j * 2 + dir) * NH + h];
;         const float dsk = dir == 0 ? F.in[I_DSK][(j * 2 + 0) * NH + h] + F.in[I_DSK][(j * 2 + 1) * NH + h] : 0.f;
;         bf16_t* yout = dir == 0 ? (bf16_t*)(F.ws + WS_XBCP) : (bf16_t*)(F.ws + WS_YB);
;         f32x4 hT[8][2];
; #pragma unroll
;         for (int nt = 0; nt < 8; ++nt) { hT[nt][0] = (f32x4){0.f, 0.f, 0.f, 0.f}; hT[nt][1] = (f32x4){0.f, 0.f, 0.f, 0.f}; }
;         {
;             const int tid0 = w * 64 + fresh_lane(); const int tid = tid0;
;             const bool isctx0 = true; const int cc0 = dir == 0 ? 0 : 1; const int row00 = MLAT + b * LCTX + cc0 * 128;
;             if (ctx_out && !(MODE & 8) && isctx0) { SCAN_DMA(CS, cm + (size_t)row00 * GNW + g * 128, GNW); SCAN_DMA(R0, bm + (size_t)row00 * GNW + g * 128, GNW); }
;         }
;         float dtr0, dtr1;
;         { const int lane0 = fresh_lane(); const int cc0 = dir == 0 ? 0 : 1, row00 = MLAT + b * LCTX + cc0 * 128;
;           dtr0 = dtb[(size_t)(row00 + lane0) * 128 + dir * 64 + h]; dtr1 = dtb[(size_t)(row00 + 64 + lane0) * 128 + dir * 64 + h]; }
;         bf16x8 xf[2][4];
;         { const int lane0 = fresh_lane(), fr0 = lane0 & 15, fq0 = lane0 >> 4; const int cc0 = dir == 0 ? 0 : 1;
;           const bf16_t* xl0 = xst + (size_t)NB * DI * LSEQ + ((size_t)(b * DI + h * 64 + ph * 32)) * LCTX + cc0 * 128 + (size_t)fr0 * LCTX + 8 * fq0;
; #pragma unroll
;           for (int pt = 0; pt < 2; ++pt)
; #pragma unroll
;               for (int ks = 0; ks < 4; ++ks) xf[pt][ks] = *(const bf16x8*)(xl0 + (size_t)(16 * pt) * LCTX + 32 * ks); }
.LBB0_479:
	s_waitcnt vmcnt(0)
	v_mul_f32_e32 v0, 0x3fb8aa3b, v1
	v_rndne_f32_e32 v2, v0
	s_mov_b32 s4, 0x3fb8aa3b
	v_sub_f32_e32 v3, v0, v2
	v_fma_f32 v0, v1, s4, -v0
	v_fmac_f32_e32 v0, 0x32a5705f, v1
	v_add_f32_e32 v0, v3, v0
	v_exp_f32_e32 v0, v0
	v_cvt_i32_f32_e32 v2, v2
	s_add_u32 s15, s66, s0
	s_mov_b32 s0, 0xc2ce8ed0
	v_cmp_ngt_f32_e32 vcc, s0, v1
	v_ldexp_f32 v2, v0, v2
	s_mov_b32 s0, 0x42b17218
	v_cndmask_b32_e32 v2, 0, v2, vcc
	v_cmp_nlt_f32_e32 vcc, s0, v1
	v_mov_b32_e32 v1, 0x7f800000
	v_readlane_b32 s46, v252, 60
	v_cndmask_b32_e32 v1, v1, v2, vcc
	v_mul_f32_e32 v204, 0xbfb8aa3b, v1
	v_mbcnt_lo_u32_b32 v1, -1, 0
	v_mbcnt_hi_u32_b32 v1, -1, v1
	v_readlane_b32 s47, v252, 61
	v_add_u32_e32 v2, s40, v1
	v_ashrrev_i32_e32 v3, 31, v2
	v_lshlrev_b64 v[4:5], 9, v[2:3]
	v_add_u32_e32 v2, 64, v2
	v_ashrrev_i32_e32 v3, 31, v2
	v_lshlrev_b64 v[2:3], 9, v[2:3]
	s_addc_u32 s17, s67, s1
	v_lshl_add_u64 v[4:5], s[46:47], 0, v[4:5]
	s_lshl_b32 s0, s11, 2
	s_mov_b32 s1, s92
	v_lshl_add_u64 v[2:3], s[46:47], 0, v[2:3]
	v_lshl_add_u64 v[4:5], v[4:5], 0, s[0:1]
	v_lshl_add_u64 v[2:3], v[2:3], 0, s[0:1]
	s_lshl_b32 s1, s10, 12
	s_lshl_b32 s4, s6, 6
	s_add_i32 s4, s4, s1
	s_lshl_b32 s1, s101, 5
	s_and_b32 s26, s1, 32
	s_or_b32 s44, s4, s26
	s_ashr_i32 s45, s44, 31
	s_lshl_b32 s34, s6, 2
	s_mov_b32 s35, s92
	s_lshl_b64 s[4:5], s[44:45], 9
	v_readlane_b32 s1, v253, 19
	v_lshl_add_u64 v[4:5], v[4:5], 0, s[34:35]
	s_add_u32 s30, s1, s4
	v_readlane_b32 s1, v253, 20
	v_lshl_add_u64 v[2:3], v[2:3], 0, s[34:35]
	global_load_dword v189, v[4:5], off
	global_load_dword v193, v[2:3], off
	v_mbcnt_lo_u32_b32 v1, -1, 0
	v_mbcnt_hi_u32_b32 v1, -1, v1
	s_addc_u32 s31, s1, s5
	s_lshl_b32 s1, s14, 1
	s_add_u32 s4, s30, s1
	v_lshlrev_b32_e32 v2, 9, v1
	v_ashrrev_i32_e32 v1, 1, v1
	s_addc_u32 s5, s31, 0
	v_and_b32_e32 v176, 0x1e00, v2
	v_and_b32_e32 v4, -8, v1
	v_lshl_add_u64 v[2:3], s[4:5], 0, v[176:177]
	v_ashrrev_i32_e32 v5, 31, v4
	v_lshl_add_u64 v[2:3], v[4:5], 1, v[2:3]
	s_movk_i32 s1, 0x2000
	global_load_dwordx4 v[140:143], v[2:3], off nt
	global_load_dwordx4 v[136:139], v[2:3], off offset:64 nt
	global_load_dwordx4 v[100:103], v[2:3], off offset:128 nt
	global_load_dwordx4 v[8:11], v[2:3], off offset:192 nt
	v_add_co_u32_e32 v2, vcc, s1, v2
	s_add_u32 s0, s46, s0
	s_nop 0
	v_addc_co_u32_e32 v3, vcc, 0, v3, vcc
	global_load_dwordx4 v[144:147], v[2:3], off nt
	global_load_dwordx4 v[76:79], v[2:3], off offset:64 nt
	global_load_dwordx4 v[48:51], v[2:3], off offset:128 nt
	global_load_dwordx4 v[44:47], v[2:3], off offset:192 nt
	s_addc_u32 s1, s47, 0
	s_add_u32 s34, s0, s34
	s_addc_u32 s35, s1, 0
	s_lshl_b32 s81, s10, 11
	s_lshl_b64 s[0:1], s[44:45], 12
	v_readlane_b32 s5, v253, 15
	s_add_u32 s96, s5, s0
	v_readlane_b32 s0, v253, 16
	s_addc_u32 s97, s0, s1
	s_lshl_b32 s0, s10, 10
	s_add_i32 s0, s42, s0
	s_ashr_i32 s1, s0, 31
	s_lshl_b64 s[10:11], s[0:1], 9
	v_readlane_b32 s5, v253, 21
	s_add_u32 s50, s5, s10
	v_readlane_b32 s5, v253, 22
	s_addc_u32 s51, s5, s11
	s_lshl_b64 s[0:1], s[0:1], 12
	v_readlane_b32 s5, v253, 13
	s_add_u32 s10, s5, s0
	v_readlane_b32 s0, v253, 14
	s_addc_u32 s11, s0, s1
	s_and_b64 s[0:1], s[38:39], exec
	s_cselect_b32 s0, 0x7c, 0
	s_add_i32 s72, s18, s0
	s_lshl_b32 s0, s6, 7
	s_add_u32 s0, s15, s0
	s_addc_u32 s1, s17, 0
	s_lshl_b32 s5, s26, 1
	s_add_u32 s0, s0, s5
	s_addc_u32 s1, s1, 0
	s_xor_b32 s76, s40, 0x80
	s_lshl_b64 s[14:15], s[42:43], 1
	v_readlane_b32 s5, v253, 11
	s_add_u32 s77, s5, s14
	v_readlane_b32 s5, v253, 12
	s_addc_u32 s73, s5, s15
	v_readlane_b32 s26, v253, 7
	v_readlane_b32 s27, v253, 8
	s_add_u32 s74, s26, s14
	s_addc_u32 s75, s27, s15
	s_and_b64 s[14:15], s[38:39], exec
	s_movk_i32 s5, 0xfc
	s_cselect_b32 s5, s5, 0x80
	s_add_i32 s14, s18, s5
	s_and_b64 s[40:41], s[38:39], exec
	s_movk_i32 s5, 0x17c
	s_cselect_b32 s5, s5, 0x100
	s_add_i32 s15, s18, s5
	s_and_b64 s[40:41], s[38:39], exec
	s_movk_i32 s5, 0x1fc
	v_mov_b32_e32 v0, 0
	s_cselect_b32 s5, s5, 0x180
	s_mov_b32 s4, 0
	s_add_i32 s6, s18, s5
	s_xor_b32 s7, s7, 1
	v_mov_b32_e32 v1, v0
	v_mov_b32_e32 v2, v0
	v_mov_b32_e32 v3, v0
	v_mov_b32_e32 v4, v0
	v_mov_b32_e32 v5, v0
	v_mov_b32_e32 v6, v0
	v_mov_b32_e32 v7, v0
	v_mov_b32_e32 v12, v0
	v_mov_b32_e32 v13, v0
	v_mov_b32_e32 v14, v0
	v_mov_b32_e32 v15, v0
	v_mov_b32_e32 v16, v0
	v_mov_b32_e32 v17, v0
	v_mov_b32_e32 v18, v0
	v_mov_b32_e32 v19, v0
	v_mov_b32_e32 v20, v0
	v_mov_b32_e32 v21, v0
	v_mov_b32_e32 v22, v0
	v_mov_b32_e32 v23, v0
	v_mov_b32_e32 v24, v0
	v_mov_b32_e32 v25, v0
	v_mov_b32_e32 v26, v0
	v_mov_b32_e32 v27, v0
	v_mov_b32_e32 v28, v0
	v_mov_b32_e32 v29, v0
	v_mov_b32_e32 v30, v0
	v_mov_b32_e32 v31, v0
	v_mov_b32_e32 v32, v0
	v_mov_b32_e32 v33, v0
	v_mov_b32_e32 v34, v0
	v_mov_b32_e32 v35, v0
	v_mov_b32_e32 v36, v0
	v_mov_b32_e32 v37, v0
	v_mov_b32_e32 v38, v0
	v_mov_b32_e32 v39, v0
	v_mov_b32_e32 v40, v0
	v_mov_b32_e32 v41, v0
	v_mov_b32_e32 v42, v0
	v_mov_b32_e32 v43, v0
	v_mov_b32_e32 v52, v0
	v_mov_b32_e32 v53, v0
	v_mov_b32_e32 v54, v0
	v_mov_b32_e32 v55, v0
	v_mov_b32_e32 v56, v0
	v_mov_b32_e32 v57, v0
	v_mov_b32_e32 v58, v0
	v_mov_b32_e32 v59, v0
	v_mov_b32_e32 v60, v0
	v_mov_b32_e32 v61, v0
	v_mov_b32_e32 v62, v0
	v_mov_b32_e32 v63, v0
	v_mov_b32_e32 v64, v0
	v_mov_b32_e32 v65, v0
	v_mov_b32_e32 v66, v0
	v_mov_b32_e32 v67, v0
	v_mov_b32_e32 v68, v0
	v_mov_b32_e32 v69, v0
	v_mov_b32_e32 v70, v0
	v_mov_b32_e32 v71, v0
	v_mov_b32_e32 v72, v0
	v_mov_b32_e32 v73, v0
	v_mov_b32_e32 v74, v0
	v_mov_b32_e32 v75, v0
	s_branch .LBB0_482

; __device__ __forceinline__ u32x4 pack8(const float (&f)[8]) { u32x4 w; w.x = cvt_pk_bf16(f[0], f[1]); w.y = cvt_pk_bf16(f[2], f[3]); w.z = cvt_pk_bf16(f[4], f[5]); w.w = cvt_pk_bf16(f[6], f[7]); return w; }
; template <int MODE> __device__ __forceinline__ void ssd_scan_phase(Frame& F, int j, bool ctx_out) {
;     ...
;             if (!(MODE & 4)) {
;                 const float dec = exp2f(tot);
; #pragma unroll
;                 for (int nt = 0; nt < 8; ++nt) { hT[nt][0] *= dec; hT[nt][1] *= dec; }
;                 bf16x8 xw[2][4];
; #pragma unroll
;                 for (int ks = 0; ks < 4; ++ks) { const float sck = __builtin_amdgcn_exp2f(tot - tab[dir == 0 ? 32 * ks + 31 : 32 * ks]);
; #pragma unroll
;                     for (int pt = 0; pt < 2; ++pt) { float xv[8]; unpack8(__builtin_bit_cast(u32x4, xs2[pt][ks]), xv);
; #pragma unroll
;                         for (int e = 0; e < 8; ++e) xv[e] *= sck;
;                         xw[pt][ks] = __builtin_bit_cast(bf16x8, pack8(xv)); } }
.LBB0_481:
	v_mov_b32_e32 v8, 0xc2fc0000
	v_cmp_lt_f32_e32 vcc, s86, v8
	s_and_b64 s[42:43], vcc, exec
	s_cselect_b32 s4, 0xffffffc0, 0
	v_cndmask_b32_e32 v8, 0, v243, vcc
	v_add_f32_e32 v8, s86, v8
	v_exp_f32_e32 v8, v8
	v_lshlrev_b32_e32 v10, 16, v92
	v_and_b32_e32 v11, 0xffff0000, v92
	v_lshlrev_b32_e32 v92, 16, v95
	v_ldexp_f32 v8, v8, s4
	v_pk_mul_f32 v[2:3], v[2:3], v[8:9] op_sel_hi:[1,0]
	v_pk_mul_f32 v[0:1], v[0:1], v[8:9] op_sel_hi:[1,0]
	v_pk_mul_f32 v[6:7], v[6:7], v[8:9] op_sel_hi:[1,0]
	v_pk_mul_f32 v[4:5], v[4:5], v[8:9] op_sel_hi:[1,0]
	v_pk_mul_f32 v[106:107], v[14:15], v[8:9] op_sel_hi:[1,0]
	v_pk_mul_f32 v[104:105], v[12:13], v[8:9] op_sel_hi:[1,0]
	v_pk_mul_f32 v[14:15], v[18:19], v[8:9] op_sel_hi:[1,0]
	v_pk_mul_f32 v[12:13], v[16:17], v[8:9] op_sel_hi:[1,0]
	v_pk_mul_f32 v[22:23], v[22:23], v[8:9] op_sel_hi:[1,0]
	v_pk_mul_f32 v[20:21], v[20:21], v[8:9] op_sel_hi:[1,0]
	v_pk_mul_f32 v[26:27], v[26:27], v[8:9] op_sel_hi:[1,0]
	v_pk_mul_f32 v[24:25], v[24:25], v[8:9] op_sel_hi:[1,0]
	v_pk_mul_f32 v[30:31], v[30:31], v[8:9] op_sel_hi:[1,0]
	v_pk_mul_f32 v[28:29], v[28:29], v[8:9] op_sel_hi:[1,0]
	v_pk_mul_f32 v[34:35], v[34:35], v[8:9] op_sel_hi:[1,0]
	v_pk_mul_f32 v[32:33], v[32:33], v[8:9] op_sel_hi:[1,0]
	v_pk_mul_f32 v[38:39], v[38:39], v[8:9] op_sel_hi:[1,0]
	v_pk_mul_f32 v[36:37], v[36:37], v[8:9] op_sel_hi:[1,0]
	v_pk_mul_f32 v[42:43], v[42:43], v[8:9] op_sel_hi:[1,0]
	v_pk_mul_f32 v[40:41], v[40:41], v[8:9] op_sel_hi:[1,0]
	v_pk_mul_f32 v[54:55], v[54:55], v[8:9] op_sel_hi:[1,0]
	v_pk_mul_f32 v[52:53], v[52:53], v[8:9] op_sel_hi:[1,0]
	v_pk_mul_f32 v[58:59], v[58:59], v[8:9] op_sel_hi:[1,0]
	v_pk_mul_f32 v[56:57], v[56:57], v[8:9] op_sel_hi:[1,0]
	v_pk_mul_f32 v[62:63], v[62:63], v[8:9] op_sel_hi:[1,0]
	v_pk_mul_f32 v[60:61], v[60:61], v[8:9] op_sel_hi:[1,0]
	v_pk_mul_f32 v[66:67], v[66:67], v[8:9] op_sel_hi:[1,0]
	v_pk_mul_f32 v[64:65], v[64:65], v[8:9] op_sel_hi:[1,0]
	v_pk_mul_f32 v[70:71], v[70:71], v[8:9] op_sel_hi:[1,0]
	v_pk_mul_f32 v[68:69], v[68:69], v[8:9] op_sel_hi:[1,0]
	v_pk_mul_f32 v[74:75], v[74:75], v[8:9] op_sel_hi:[1,0]
	v_pk_mul_f32 v[72:73], v[72:73], v[8:9] op_sel_hi:[1,0]
	v_mov_b32_e32 v8, s72
	ds_read_b32 v8, v8
	v_lshlrev_b32_e32 v16, 16, v93
	v_and_b32_e32 v17, 0xffff0000, v93
	v_lshlrev_b32_e32 v18, 16, v94
	v_and_b32_e32 v19, 0xffff0000, v94
	s_waitcnt lgkmcnt(0)
	v_sub_f32_e32 v8, s86, v8
	v_exp_f32_e32 v8, v8
	v_and_b32_e32 v93, 0xffff0000, v95
	s_sub_i32 s17, 17, s5
	v_lshl_add_u32 v120, v176, 8, s26
	v_pk_mul_f32 v[10:11], v[8:9], v[10:11] op_sel_hi:[0,1]
	v_pk_mul_f32 v[16:17], v[8:9], v[16:17] op_sel_hi:[0,1]
	v_pk_mul_f32 v[18:19], v[8:9], v[18:19] op_sel_hi:[0,1]
	v_pk_mul_f32 v[100:101], v[8:9], v[92:93] op_sel_hi:[0,1]
	v_cvt_pk_bf16_f32 v92, v10, v11
	v_cvt_pk_bf16_f32 v93, v16, v17
	v_cvt_pk_bf16_f32 v94, v18, v19
	v_lshlrev_b32_e32 v10, 16, v96
	v_and_b32_e32 v11, 0xffff0000, v96
	v_lshlrev_b32_e32 v16, 16, v97
	v_and_b32_e32 v17, 0xffff0000, v97
	v_lshlrev_b32_e32 v18, 16, v98
	v_and_b32_e32 v19, 0xffff0000, v98
	v_lshlrev_b32_e32 v96, 16, v99
	v_and_b32_e32 v97, 0xffff0000, v99
	v_pk_mul_f32 v[10:11], v[8:9], v[10:11] op_sel_hi:[0,1]
	v_pk_mul_f32 v[16:17], v[8:9], v[16:17] op_sel_hi:[0,1]
	v_pk_mul_f32 v[18:19], v[8:9], v[18:19] op_sel_hi:[0,1]
	v_pk_mul_f32 v[8:9], v[8:9], v[96:97] op_sel_hi:[0,1]
	v_cvt_pk_bf16_f32 v99, v8, v9
	v_mov_b32_e32 v8, s14
	ds_read_b32 v8, v8
	v_cvt_pk_bf16_f32 v96, v10, v11
	v_cvt_pk_bf16_f32 v97, v16, v17
	v_cvt_pk_bf16_f32 v98, v18, v19
	v_lshlrev_b32_e32 v10, 16, v84
	s_waitcnt lgkmcnt(0)
	v_sub_f32_e32 v8, s86, v8
	v_exp_f32_e32 v8, v8
	v_and_b32_e32 v11, 0xffff0000, v84
	v_lshlrev_b32_e32 v16, 16, v85
	v_and_b32_e32 v17, 0xffff0000, v85
	v_lshlrev_b32_e32 v18, 16, v86
	v_and_b32_e32 v19, 0xffff0000, v86
	v_lshlrev_b32_e32 v84, 16, v87
	v_and_b32_e32 v85, 0xffff0000, v87
	v_pk_mul_f32 v[10:11], v[8:9], v[10:11] op_sel_hi:[0,1]
	v_pk_mul_f32 v[16:17], v[8:9], v[16:17] op_sel_hi:[0,1]
	v_pk_mul_f32 v[18:19], v[8:9], v[18:19] op_sel_hi:[0,1]
	v_cvt_pk_bf16_f32 v95, v100, v101
	v_pk_mul_f32 v[100:101], v[8:9], v[84:85] op_sel_hi:[0,1]
	v_cvt_pk_bf16_f32 v84, v10, v11
	v_cvt_pk_bf16_f32 v85, v16, v17
	v_cvt_pk_bf16_f32 v86, v18, v19
	v_lshlrev_b32_e32 v10, 16, v88
	v_and_b32_e32 v11, 0xffff0000, v88
	v_lshlrev_b32_e32 v16, 16, v89
	v_and_b32_e32 v17, 0xffff0000, v89
	v_lshlrev_b32_e32 v18, 16, v90
	v_and_b32_e32 v19, 0xffff0000, v90
	v_lshlrev_b32_e32 v88, 16, v91
	v_and_b32_e32 v89, 0xffff0000, v91
	v_pk_mul_f32 v[10:11], v[8:9], v[10:11] op_sel_hi:[0,1]
	v_pk_mul_f32 v[16:17], v[8:9], v[16:17] op_sel_hi:[0,1]
	v_pk_mul_f32 v[18:19], v[8:9], v[18:19] op_sel_hi:[0,1]
	v_pk_mul_f32 v[8:9], v[8:9], v[88:89] op_sel_hi:[0,1]
	v_cvt_pk_bf16_f32 v91, v8, v9
	v_mov_b32_e32 v8, s15
	ds_read_b32 v8, v8
	v_cvt_pk_bf16_f32 v88, v10, v11
	v_cvt_pk_bf16_f32 v89, v16, v17
	v_cvt_pk_bf16_f32 v90, v18, v19
	v_lshlrev_b32_e32 v10, 16, v80
	s_waitcnt lgkmcnt(0)
	v_sub_f32_e32 v8, s86, v8
	v_exp_f32_e32 v8, v8
	v_and_b32_e32 v11, 0xffff0000, v80
	v_lshlrev_b32_e32 v16, 16, v81
	v_and_b32_e32 v17, 0xffff0000, v81
	v_lshlrev_b32_e32 v18, 16, v82
	v_and_b32_e32 v19, 0xffff0000, v82
	v_lshlrev_b32_e32 v80, 16, v83
	v_and_b32_e32 v81, 0xffff0000, v83
	v_pk_mul_f32 v[10:11], v[8:9], v[10:11] op_sel_hi:[0,1]
	v_pk_mul_f32 v[16:17], v[8:9], v[16:17] op_sel_hi:[0,1]
	v_pk_mul_f32 v[18:19], v[8:9], v[18:19] op_sel_hi:[0,1]
	v_cvt_pk_bf16_f32 v87, v100, v101
	v_pk_mul_f32 v[100:101], v[8:9], v[80:81] op_sel_hi:[0,1]
	v_cvt_pk_bf16_f32 v80, v10, v11
	v_cvt_pk_bf16_f32 v81, v16, v17
	v_cvt_pk_bf16_f32 v82, v18, v19
	v_lshlrev_b32_e32 v10, 16, v76
	v_and_b32_e32 v11, 0xffff0000, v76
	v_lshlrev_b32_e32 v16, 16, v77
	v_and_b32_e32 v17, 0xffff0000, v77
	v_lshlrev_b32_e32 v18, 16, v78
	v_and_b32_e32 v19, 0xffff0000, v78
	v_lshlrev_b32_e32 v76, 16, v79
	v_and_b32_e32 v77, 0xffff0000, v79
	v_pk_mul_f32 v[10:11], v[8:9], v[10:11] op_sel_hi:[0,1]
	v_pk_mul_f32 v[16:17], v[8:9], v[16:17] op_sel_hi:[0,1]
	v_pk_mul_f32 v[18:19], v[8:9], v[18:19] op_sel_hi:[0,1]
	v_pk_mul_f32 v[8:9], v[8:9], v[76:77] op_sel_hi:[0,1]
	v_cvt_pk_bf16_f32 v111, v8, v9
	v_mov_b32_e32 v8, s6
	ds_read_b32 v8, v8
	v_cvt_pk_bf16_f32 v108, v10, v11
	v_cvt_pk_bf16_f32 v109, v16, v17
	v_cvt_pk_bf16_f32 v110, v18, v19
	v_lshlrev_b32_e32 v10, 16, v48
	s_waitcnt lgkmcnt(0)
; #define LAS __attribute__((address_space(3)))
;     __device__ __forceinline__ const char* b(const pg8::Unit& u) const { return (const char*)ws + boff + (size_t)u.pn * 256 * K_ * 2 + (u.kq < 0 ? 0 : u.kq * (K_ / 4) * 2); }
;     __device__ __forceinline__ const char* b(const pg8::Unit& u) const { return (const char*)ws + boff + (size_t)u.pn * 256 * D * 2; }
;     __device__ __forceinline__ const char* b(const pg8::Unit& u) const { return (const char*)ws + boff + (size_t)u.pn * 256 * D * 2; }
;     __device__ __forceinline__ const char* b(const pg8::Unit& u) const { return (const char*)ws + WS_A + ((size_t)u.pn * 256 * D + (size_t)(u.pm >> 1) * 256) * 2; }
; template <int MODE> __device__ __forceinline__ void ssd_scan_phase(Frame& F, int j, bool ctx_out) {
;     ...
;                 {
;                     const int kn = k + 1 < 18 ? k + 1 : 17; const bool isctxn = kn < 2; const int ccn = isctxn ? (dir == 0 ? kn : 1 - kn) : (dir == 0 ? kn - 2 : 17 - kn); const int Tn = isctxn ? LCTX : LSEQ;
;                     const bf16_t* xln = (isctxn ? xst + (size_t)NB * DI * LSEQ + ((size_t)(b * DI + h * 64 + ph * 32)) * LCTX + ccn * 128 : xst + ((size_t)(b * DI + h * 64 + ph * 32)) * LSEQ + ccn * 128) + (size_t)fr * Tn + 8 * fq;
; #pragma unroll
;                     for (int pt = 0; pt < 2; ++pt)
; #pragma unroll
;                         for (int ks = 0; ks < 4; ++ks) xf[pt][ks] = *(const bf16x8*)(xln + (size_t)(16 * pt) * Tn + 32 * ks); }
; #pragma unroll
;                 for (int nt = 0; nt < 8; ++nt) {
; #pragma unroll
;                     for (int ks = 0; ks < 4; ++ks) { const bf16x8 bfr = *(const LAS bf16x8*)(BS + (16 * nt + fr) * 256 + (((4 * ks + fq) ^ fr) << 4));
;                         hT[nt][0] = __builtin_amdgcn_mfma_f32_16x16x32_bf16(bfr, xw[0][ks], hT[nt][0], 0, 0, 0);
;                         hT[nt][1] = __builtin_amdgcn_mfma_f32_16x16x32_bf16(bfr, xw[1][ks], hT[nt][1], 0, 0, 0); }
	v_sub_f32_e32 v8, s86, v8
	v_exp_f32_e32 v8, v8
	v_and_b32_e32 v11, 0xffff0000, v48
	v_lshlrev_b32_e32 v16, 16, v49
	v_and_b32_e32 v17, 0xffff0000, v49
	v_lshlrev_b32_e32 v18, 16, v50
	v_and_b32_e32 v19, 0xffff0000, v50
	v_pk_mul_f32 v[10:11], v[8:9], v[10:11] op_sel_hi:[0,1]
	v_pk_mul_f32 v[16:17], v[8:9], v[16:17] op_sel_hi:[0,1]
	v_pk_mul_f32 v[18:19], v[8:9], v[18:19] op_sel_hi:[0,1]
	v_lshlrev_b32_e32 v48, 16, v51
	v_and_b32_e32 v49, 0xffff0000, v51
	v_cvt_pk_bf16_f32 v112, v10, v11
	v_cvt_pk_bf16_f32 v113, v16, v17
	v_cvt_pk_bf16_f32 v114, v18, v19
	v_lshlrev_b32_e32 v10, 16, v44
	v_and_b32_e32 v11, 0xffff0000, v44
	v_lshlrev_b32_e32 v16, 16, v45
	v_and_b32_e32 v17, 0xffff0000, v45
	v_lshlrev_b32_e32 v18, 16, v46
	v_and_b32_e32 v19, 0xffff0000, v46
	v_lshlrev_b32_e32 v44, 16, v47
	v_and_b32_e32 v45, 0xffff0000, v47
	v_pk_mul_f32 v[48:49], v[8:9], v[48:49] op_sel_hi:[0,1]
	v_pk_mul_f32 v[10:11], v[8:9], v[10:11] op_sel_hi:[0,1]
	v_pk_mul_f32 v[16:17], v[8:9], v[16:17] op_sel_hi:[0,1]
	v_pk_mul_f32 v[18:19], v[8:9], v[18:19] op_sel_hi:[0,1]
	v_pk_mul_f32 v[8:9], v[8:9], v[44:45] op_sel_hi:[0,1]
	v_cvt_pk_bf16_f32 v119, v8, v9
	v_sub_co_u32_e64 v8, s[42:43], s5, 2
	s_and_b64 s[4:5], s[38:39], exec
	v_readfirstlane_b32 s4, v8
	s_cselect_b32 s17, s4, s17
	s_and_b64 s[4:5], s[42:43], exec
	s_cselect_b32 s17, s7, s17
	s_cselect_b32 s4, 0x2000, s84
	s_cselect_b32 s27, s31, s97
	s_cselect_b32 s41, s30, s96
	s_lshl_b32 s44, s17, 7
	s_ashr_i32 s45, s44, 31
	s_lshl_b64 s[44:45], s[44:45], 1
	s_add_u32 s44, s41, s44
	s_addc_u32 s45, s27, s45
	s_and_b64 s[42:43], s[42:43], exec
	s_cselect_b32 s17, 8, 11
	v_lshlrev_b64 v[8:9], s17, v[176:177]
	v_lshl_add_u64 v[8:9], v[8:9], 1, s[44:45]
	v_cvt_pk_bf16_f32 v117, v16, v17
	s_mov_b32 s5, s92
	v_lshl_add_u64 v[16:17], v[180:181], 1, v[8:9]
	v_cvt_pk_bf16_f32 v83, v100, v101
	v_cvt_pk_bf16_f32 v116, v10, v11
	global_load_dwordx4 v[140:143], v[16:17], off nt
	global_load_dwordx4 v[136:139], v[16:17], off offset:64 nt
	global_load_dwordx4 v[100:103], v[16:17], off offset:128 nt
	global_load_dwordx4 v[8:11], v[16:17], off offset:192 nt
	v_lshl_add_u64 v[16:17], v[16:17], 0, s[4:5]
	v_cvt_pk_bf16_f32 v115, v48, v49
	global_load_dwordx4 v[144:147], v[16:17], off nt
	global_load_dwordx4 v[76:79], v[16:17], off offset:64 nt
	global_load_dwordx4 v[48:51], v[16:17], off offset:128 nt
	global_load_dwordx4 v[44:47], v[16:17], off offset:192 nt
	v_lshl_add_u32 v122, v208, 4, v120
	v_cvt_pk_bf16_f32 v118, v18, v19
	v_lshl_add_u32 v123, v207, 4, v120
	v_lshl_add_u32 v121, v206, 4, v120
	v_lshl_add_u32 v120, v205, 4, v120
	ds_read_b128 v[148:151], v122
	ds_read_b128 v[152:155], v123
	ds_read_b128 v[156:159], v121
	ds_read_b128 v[160:163], v120
	ds_read_b128 v[164:167], v122 offset:4096
	ds_read_b128 v[168:171], v123 offset:4096
	ds_read_b128 v[172:175], v121 offset:4096
	ds_read_b128 v[210:213], v120 offset:4096
	s_waitcnt lgkmcnt(7)
	v_mfma_f32_16x16x32_bf16 v[0:3], v[148:151], v[92:95], v[0:3]
	v_mfma_f32_16x16x32_bf16 v[4:7], v[148:151], v[96:99], v[4:7]
	ds_read_b128 v[148:151], v122 offset:8192
	s_waitcnt lgkmcnt(7)
	v_mfma_f32_16x16x32_bf16 v[0:3], v[152:155], v[84:87], v[0:3]
	v_mfma_f32_16x16x32_bf16 v[4:7], v[152:155], v[88:91], v[4:7]
	ds_read_b128 v[152:155], v123 offset:8192
	s_waitcnt lgkmcnt(7)
	v_mfma_f32_16x16x32_bf16 v[0:3], v[156:159], v[80:83], v[0:3]
	v_mfma_f32_16x16x32_bf16 v[4:7], v[156:159], v[108:111], v[4:7]
	ds_read_b128 v[156:159], v121 offset:8192
	s_waitcnt lgkmcnt(7)
	v_mfma_f32_16x16x32_bf16 v[0:3], v[160:163], v[112:115], v[0:3]
	v_mfma_f32_16x16x32_bf16 v[4:7], v[160:163], v[116:119], v[4:7]
	ds_read_b128 v[160:163], v120 offset:8192
	s_waitcnt lgkmcnt(7)
	v_mfma_f32_16x16x32_bf16 v[16:19], v[164:167], v[96:99], v[12:15]
	v_mfma_f32_16x16x32_bf16 v[12:15], v[164:167], v[92:95], v[104:107]
	ds_read_b128 v[164:167], v122 offset:12288
	s_waitcnt lgkmcnt(7)
	v_mfma_f32_16x16x32_bf16 v[12:15], v[168:171], v[84:87], v[12:15]
	v_mfma_f32_16x16x32_bf16 v[16:19], v[168:171], v[88:91], v[16:19]
	ds_read_b128 v[168:171], v123 offset:12288
	s_waitcnt lgkmcnt(7)
	v_mfma_f32_16x16x32_bf16 v[12:15], v[172:175], v[80:83], v[12:15]
	v_mfma_f32_16x16x32_bf16 v[16:19], v[172:175], v[108:111], v[16:19]
	ds_read_b128 v[172:175], v121 offset:12288
	s_waitcnt lgkmcnt(7)
	v_mfma_f32_16x16x32_bf16 v[12:15], v[210:213], v[112:115], v[12:15]
	v_mfma_f32_16x16x32_bf16 v[16:19], v[210:213], v[116:119], v[16:19]
	ds_read_b128 v[210:213], v120 offset:12288
	s_waitcnt lgkmcnt(7)
; #define LAS __attribute__((address_space(3)))
; template <int MODE> __device__ __forceinline__ void ssd_scan_phase(Frame& F, int j, bool ctx_out) {
;     ...
;         for (int k = 0; k < 18; ++k) {
;     ...
;                 for (int nt = 0; nt < 8; ++nt) {
; #pragma unroll
;                     for (int ks = 0; ks < 4; ++ks) { const bf16x8 bfr = *(const LAS bf16x8*)(BS + (16 * nt + fr) * 256 + (((4 * ks + fq) ^ fr) << 4));
;                         hT[nt][0] = __builtin_amdgcn_mfma_f32_16x16x32_bf16(bfr, xw[0][ks], hT[nt][0], 0, 0, 0);
;                         hT[nt][1] = __builtin_amdgcn_mfma_f32_16x16x32_bf16(bfr, xw[1][ks], hT[nt][1], 0, 0, 0); }
;                     if (nt & 1) __builtin_amdgcn_sched_barrier(0);
;                 }
	v_mfma_f32_16x16x32_bf16 v[20:23], v[148:151], v[92:95], v[20:23]
	v_mfma_f32_16x16x32_bf16 v[24:27], v[148:151], v[96:99], v[24:27]
	ds_read_b128 v[148:151], v122 offset:16384
	s_waitcnt lgkmcnt(7)
	v_mfma_f32_16x16x32_bf16 v[20:23], v[152:155], v[84:87], v[20:23]
	v_mfma_f32_16x16x32_bf16 v[24:27], v[152:155], v[88:91], v[24:27]
	ds_read_b128 v[152:155], v123 offset:16384
	s_waitcnt lgkmcnt(7)
	v_mfma_f32_16x16x32_bf16 v[20:23], v[156:159], v[80:83], v[20:23]
	v_mfma_f32_16x16x32_bf16 v[24:27], v[156:159], v[108:111], v[24:27]
	ds_read_b128 v[156:159], v121 offset:16384
	s_waitcnt lgkmcnt(7)
	v_mfma_f32_16x16x32_bf16 v[20:23], v[160:163], v[112:115], v[20:23]
	v_mfma_f32_16x16x32_bf16 v[24:27], v[160:163], v[116:119], v[24:27]
	ds_read_b128 v[160:163], v120 offset:16384
	s_waitcnt lgkmcnt(7)
	v_mfma_f32_16x16x32_bf16 v[28:31], v[164:167], v[92:95], v[28:31]
	v_mfma_f32_16x16x32_bf16 v[32:35], v[164:167], v[96:99], v[32:35]
	ds_read_b128 v[164:167], v122 offset:20480
	s_waitcnt lgkmcnt(7)
	v_mfma_f32_16x16x32_bf16 v[28:31], v[168:171], v[84:87], v[28:31]
	v_mfma_f32_16x16x32_bf16 v[32:35], v[168:171], v[88:91], v[32:35]
	ds_read_b128 v[168:171], v123 offset:20480
	s_waitcnt lgkmcnt(7)
	v_mfma_f32_16x16x32_bf16 v[28:31], v[172:175], v[80:83], v[28:31]
	v_mfma_f32_16x16x32_bf16 v[32:35], v[172:175], v[108:111], v[32:35]
	ds_read_b128 v[172:175], v121 offset:20480
	s_waitcnt lgkmcnt(7)
	v_mfma_f32_16x16x32_bf16 v[28:31], v[210:213], v[112:115], v[28:31]
	v_mfma_f32_16x16x32_bf16 v[32:35], v[210:213], v[116:119], v[32:35]
	ds_read_b128 v[210:213], v120 offset:20480
	s_waitcnt lgkmcnt(7)
	v_mfma_f32_16x16x32_bf16 v[36:39], v[148:151], v[92:95], v[36:39]
	v_mfma_f32_16x16x32_bf16 v[40:43], v[148:151], v[96:99], v[40:43]
	ds_read_b128 v[148:151], v122 offset:24576
	s_waitcnt lgkmcnt(7)
	v_mfma_f32_16x16x32_bf16 v[36:39], v[152:155], v[84:87], v[36:39]
	v_mfma_f32_16x16x32_bf16 v[40:43], v[152:155], v[88:91], v[40:43]
	ds_read_b128 v[152:155], v123 offset:24576
	s_waitcnt lgkmcnt(7)
	v_mfma_f32_16x16x32_bf16 v[36:39], v[156:159], v[80:83], v[36:39]
	v_mfma_f32_16x16x32_bf16 v[40:43], v[156:159], v[108:111], v[40:43]
	ds_read_b128 v[156:159], v121 offset:24576
	s_waitcnt lgkmcnt(7)
	v_mfma_f32_16x16x32_bf16 v[36:39], v[160:163], v[112:115], v[36:39]
	v_mfma_f32_16x16x32_bf16 v[40:43], v[160:163], v[116:119], v[40:43]
	ds_read_b128 v[160:163], v120 offset:24576
	s_waitcnt lgkmcnt(7)
	v_mfma_f32_16x16x32_bf16 v[52:55], v[164:167], v[92:95], v[52:55]
	v_mfma_f32_16x16x32_bf16 v[56:59], v[164:167], v[96:99], v[56:59]
	ds_read_b128 v[164:167], v122 offset:28672
	s_waitcnt lgkmcnt(7)
	v_mfma_f32_16x16x32_bf16 v[52:55], v[168:171], v[84:87], v[52:55]
	v_mfma_f32_16x16x32_bf16 v[56:59], v[168:171], v[88:91], v[56:59]
	ds_read_b128 v[168:171], v123 offset:28672
	s_waitcnt lgkmcnt(7)
	v_mfma_f32_16x16x32_bf16 v[52:55], v[172:175], v[80:83], v[52:55]
	v_mfma_f32_16x16x32_bf16 v[56:59], v[172:175], v[108:111], v[56:59]
	ds_read_b128 v[172:175], v121 offset:28672
	s_waitcnt lgkmcnt(7)
	v_mfma_f32_16x16x32_bf16 v[52:55], v[210:213], v[112:115], v[52:55]
	v_mfma_f32_16x16x32_bf16 v[56:59], v[210:213], v[116:119], v[56:59]
	ds_read_b128 v[210:213], v120 offset:28672
	s_waitcnt lgkmcnt(7)
	v_mfma_f32_16x16x32_bf16 v[60:63], v[148:151], v[92:95], v[60:63]
	v_mfma_f32_16x16x32_bf16 v[64:67], v[148:151], v[96:99], v[64:67]
	s_waitcnt lgkmcnt(6)
	v_mfma_f32_16x16x32_bf16 v[60:63], v[152:155], v[84:87], v[60:63]
	v_mfma_f32_16x16x32_bf16 v[64:67], v[152:155], v[88:91], v[64:67]
	s_waitcnt lgkmcnt(5)
	v_mfma_f32_16x16x32_bf16 v[60:63], v[156:159], v[80:83], v[60:63]
	v_mfma_f32_16x16x32_bf16 v[64:67], v[156:159], v[108:111], v[64:67]
	s_waitcnt lgkmcnt(4)
	v_mfma_f32_16x16x32_bf16 v[60:63], v[160:163], v[112:115], v[60:63]
	v_mfma_f32_16x16x32_bf16 v[64:67], v[160:163], v[116:119], v[64:67]
	s_waitcnt lgkmcnt(3)
	v_mfma_f32_16x16x32_bf16 v[68:71], v[164:167], v[92:95], v[68:71]
	v_mfma_f32_16x16x32_bf16 v[72:75], v[164:167], v[96:99], v[72:75]
	s_waitcnt lgkmcnt(2)
	v_mfma_f32_16x16x32_bf16 v[68:71], v[168:171], v[84:87], v[68:71]
	v_mfma_f32_16x16x32_bf16 v[72:75], v[168:171], v[88:91], v[72:75]
	s_waitcnt lgkmcnt(1)
	v_mfma_f32_16x16x32_bf16 v[68:71], v[172:175], v[80:83], v[68:71]
	v_mfma_f32_16x16x32_bf16 v[72:75], v[172:175], v[108:111], v[72:75]
	s_waitcnt lgkmcnt(0)
	v_mfma_f32_16x16x32_bf16 v[68:71], v[210:213], v[112:115], v[68:71]
	v_mfma_f32_16x16x32_bf16 v[72:75], v[210:213], v[116:119], v[72:75]
	s_cmp_eq_u32 s40, 18
	s_mov_b32 s4, s40
	s_cbranch_scc1 .LBB0_471

; #define LAS __attribute__((address_space(3)))
; __device__ __forceinline__ u32x4 pack8(const float (&f)[8]) { u32x4 w; w.x = cvt_pk_bf16(f[0], f[1]); w.y = cvt_pk_bf16(f[2], f[3]); w.z = cvt_pk_bf16(f[4], f[5]); w.w = cvt_pk_bf16(f[6], f[7]); return w; }
; #define SCAN_DMA(dstbase, srcptr_row0, pitch_elems) do { _Pragma("unroll") for (int q_ = 0; q_ < 4; ++q_) { const int idx_ = tid + 512 * q_, row_ = idx_ >> 4, c16_ = (idx_ & 15) ^ (row_ & 15); \
;         __builtin_amdgcn_global_load_lds((const unsigned*)((srcptr_row0) + (size_t)row_ * (pitch_elems) + c16_ * 8), (LAS unsigned*)((dstbase) + (w * 64 + 512 * q_) * 16), 16, 0, 0); } } while (0)
; template <int MODE> __device__ __forceinline__ void ssd_scan_phase(Frame& F, int j, bool ctx_out) {
;     ...
;             bf16x8 xs2[2][4];
; #pragma unroll
;             for (int ks = 0; ks < 4; ++ks) { const f32x4 fa = *(const LAS f32x4*)(tab + 384 + 32 * ks + 8 * fq), fb = *(const LAS f32x4*)(tab + 384 + 32 * ks + 8 * fq + 4);
; #pragma unroll
;                 for (int pt = 0; pt < 2; ++pt) { float xv[8]; unpack8(__builtin_bit_cast(u32x4, xf[pt][ks]), xv);
;                     xv[0] *= fa.x; xv[1] *= fa.y; xv[2] *= fa.z; xv[3] *= fa.w; xv[4] *= fb.x; xv[5] *= fb.y; xv[6] *= fb.z; xv[7] *= fb.w;
;                     xs2[pt][ks] = __builtin_bit_cast(bf16x8, pack8(xv)); } }
;     ...
;             __syncthreads();
;             if (!(MODE & 8)) SCAN_DMA(BS, btp, T);
.LBB0_487:
	v_lshlrev_b32_e32 v92, 16, v140
	v_and_b32_e32 v93, 0xffff0000, v140
	v_lshlrev_b32_e32 v94, 16, v141
	v_and_b32_e32 v95, 0xffff0000, v141
	v_lshlrev_b32_e32 v120, 16, v142
	v_and_b32_e32 v121, 0xffff0000, v142
	s_waitcnt lgkmcnt(7)
	v_pk_mul_f32 v[92:93], v[96:97], v[92:93]
	v_pk_mul_f32 v[94:95], v[98:99], v[94:95]
	s_waitcnt lgkmcnt(6)
	v_pk_mul_f32 v[120:121], v[84:85], v[120:121]
	v_cvt_pk_bf16_f32 v92, v92, v93
	v_cvt_pk_bf16_f32 v93, v94, v95
	v_cvt_pk_bf16_f32 v94, v120, v121
	v_lshlrev_b32_e32 v120, 16, v144
	v_and_b32_e32 v121, 0xffff0000, v144
	v_pk_mul_f32 v[96:97], v[96:97], v[120:121]
	v_lshlrev_b32_e32 v120, 16, v145
	v_and_b32_e32 v121, 0xffff0000, v145
	v_pk_mul_f32 v[98:99], v[98:99], v[120:121]
	v_lshlrev_b32_e32 v120, 16, v146
	v_and_b32_e32 v121, 0xffff0000, v146
	v_lshlrev_b32_e32 v122, 16, v143
	v_and_b32_e32 v123, 0xffff0000, v143
	v_pk_mul_f32 v[84:85], v[84:85], v[120:121]
	v_lshlrev_b32_e32 v120, 16, v147
	v_and_b32_e32 v121, 0xffff0000, v147
	v_pk_mul_f32 v[122:123], v[86:87], v[122:123]
	v_pk_mul_f32 v[86:87], v[86:87], v[120:121]
	v_cvt_pk_bf16_f32 v96, v96, v97
	v_cvt_pk_bf16_f32 v97, v98, v99
	v_cvt_pk_bf16_f32 v98, v84, v85
	v_cvt_pk_bf16_f32 v99, v86, v87
	v_lshlrev_b32_e32 v84, 16, v136
	v_and_b32_e32 v85, 0xffff0000, v136
	v_lshlrev_b32_e32 v86, 16, v137
	v_and_b32_e32 v87, 0xffff0000, v137
	v_lshlrev_b32_e32 v120, 16, v138
	v_and_b32_e32 v121, 0xffff0000, v138
	s_waitcnt lgkmcnt(5)
	v_pk_mul_f32 v[84:85], v[88:89], v[84:85]
	v_pk_mul_f32 v[86:87], v[90:91], v[86:87]
	s_waitcnt lgkmcnt(4)
	v_pk_mul_f32 v[120:121], v[80:81], v[120:121]
	v_cvt_pk_bf16_f32 v84, v84, v85
	v_cvt_pk_bf16_f32 v85, v86, v87
	v_cvt_pk_bf16_f32 v86, v120, v121
	v_lshlrev_b32_e32 v120, 16, v76
	v_and_b32_e32 v121, 0xffff0000, v76
	v_lshlrev_b32_e32 v76, 16, v77
	v_and_b32_e32 v77, 0xffff0000, v77
	v_pk_mul_f32 v[76:77], v[90:91], v[76:77]
	v_lshlrev_b32_e32 v90, 16, v78
	v_and_b32_e32 v91, 0xffff0000, v78
	v_lshlrev_b32_e32 v78, 16, v79
	v_and_b32_e32 v79, 0xffff0000, v79
	v_pk_mul_f32 v[88:89], v[88:89], v[120:121]
	v_pk_mul_f32 v[80:81], v[80:81], v[90:91]
	v_pk_mul_f32 v[78:79], v[82:83], v[78:79]
	v_cvt_pk_bf16_f32 v95, v122, v123
	v_lshlrev_b32_e32 v122, 16, v139
	v_and_b32_e32 v123, 0xffff0000, v139
	v_cvt_pk_bf16_f32 v88, v88, v89
	v_cvt_pk_bf16_f32 v89, v76, v77
	v_cvt_pk_bf16_f32 v90, v80, v81
	v_cvt_pk_bf16_f32 v91, v78, v79
	v_lshlrev_b32_e32 v76, 16, v100
	v_and_b32_e32 v77, 0xffff0000, v100
	v_lshlrev_b32_e32 v78, 16, v101
	v_and_b32_e32 v79, 0xffff0000, v101
	v_lshlrev_b32_e32 v80, 16, v102
	v_and_b32_e32 v81, 0xffff0000, v102
	v_pk_mul_f32 v[122:123], v[82:83], v[122:123]
	s_waitcnt lgkmcnt(3)
	v_pk_mul_f32 v[76:77], v[116:117], v[76:77]
	v_pk_mul_f32 v[78:79], v[118:119], v[78:79]
	s_waitcnt lgkmcnt(2)
	v_pk_mul_f32 v[82:83], v[112:113], v[80:81]
	v_lshlrev_b32_e32 v80, 16, v103
	v_and_b32_e32 v81, 0xffff0000, v103
	v_pk_mul_f32 v[120:121], v[114:115], v[80:81]
	v_cvt_pk_bf16_f32 v80, v76, v77
	v_cvt_pk_bf16_f32 v81, v78, v79
	v_lshlrev_b32_e32 v76, 16, v48
	v_and_b32_e32 v77, 0xffff0000, v48
	v_lshlrev_b32_e32 v48, 16, v49
	v_and_b32_e32 v49, 0xffff0000, v49
	v_lshlrev_b32_e32 v78, 16, v50
	v_and_b32_e32 v79, 0xffff0000, v50
	v_lshlrev_b32_e32 v50, 16, v51
	v_and_b32_e32 v51, 0xffff0000, v51
	v_pk_mul_f32 v[76:77], v[116:117], v[76:77]
	v_pk_mul_f32 v[48:49], v[118:119], v[48:49]
	v_pk_mul_f32 v[78:79], v[112:113], v[78:79]
	v_pk_mul_f32 v[50:51], v[114:115], v[50:51]
	v_cvt_pk_bf16_f32 v76, v76, v77
	v_cvt_pk_bf16_f32 v77, v48, v49
	v_cvt_pk_bf16_f32 v78, v78, v79
	v_cvt_pk_bf16_f32 v79, v50, v51
	v_lshlrev_b32_e32 v48, 16, v8
	v_and_b32_e32 v49, 0xffff0000, v8
	v_lshlrev_b32_e32 v50, 16, v9
	v_and_b32_e32 v51, 0xffff0000, v9
	v_lshlrev_b32_e32 v112, 16, v10
	v_and_b32_e32 v113, 0xffff0000, v10
	s_waitcnt lgkmcnt(1)
	v_pk_mul_f32 v[48:49], v[108:109], v[48:49]
	v_pk_mul_f32 v[50:51], v[110:111], v[50:51]
	s_waitcnt lgkmcnt(0)
	v_pk_mul_f32 v[112:113], v[104:105], v[112:113]
	v_cvt_pk_bf16_f32 v48, v48, v49
	v_cvt_pk_bf16_f32 v49, v50, v51
	v_cvt_pk_bf16_f32 v50, v112, v113
	v_lshlrev_b32_e32 v112, 16, v44
	v_and_b32_e32 v113, 0xffff0000, v44
	v_lshlrev_b32_e32 v44, 16, v45
	v_and_b32_e32 v45, 0xffff0000, v45
	s_and_b64 s[46:47], exec, s[46:47]
	v_pk_mul_f32 v[110:111], v[110:111], v[44:45]
	v_lshlrev_b32_e32 v44, 16, v46
	v_and_b32_e32 v45, 0xffff0000, v46
	s_cselect_b32 s17, 1, 17
	v_lshlrev_b32_e32 v114, 16, v11
	v_and_b32_e32 v115, 0xffff0000, v11
	v_pk_mul_f32 v[104:105], v[104:105], v[44:45]
	v_lshlrev_b32_e32 v44, 16, v47
	v_and_b32_e32 v45, 0xffff0000, v47
	s_cselect_b32 s27, s4, s93
	s_sub_i32 s17, s17, s4
	v_pk_mul_f32 v[114:115], v[106:107], v[114:115]
	v_pk_mul_f32 v[106:107], v[106:107], v[44:45]
	s_and_b64 s[46:47], s[38:39], exec
	v_cvt_pk_bf16_f32 v47, v106, v107
	v_add_u32_e32 v106, s33, v209
	s_cselect_b32 s43, s27, s17
	v_ashrrev_i32_e32 v188, 4, v106
	s_lshl_b32 s17, s43, 8
	v_xor_b32_e32 v107, v188, v209
	s_add_u32 s46, s48, s17
	v_lshlrev_b32_e32 v107, 3, v107
	s_addc_u32 s47, s49, 0
	v_cvt_pk_bf16_f32 v46, v104, v105
	v_mad_i64_i32 v[104:105], s[48:49], s42, v188, 0
	v_and_b32_e32 v107, 0x78, v107
	v_lshl_add_u64 v[104:105], v[104:105], 1, s[46:47]
	v_lshlrev_b32_e32 v182, 1, v107
	v_mov_b32_e32 v183, v177
	s_add_i32 s17, s26, s3
	v_lshl_add_u64 v[104:105], v[104:105], 0, v[182:183]
	s_mov_b32 m0, s17
	s_barrier
; #define LAS __attribute__((address_space(3)))
; __device__ __forceinline__ unsigned cvt_pk_bf16(float lo, float hi) { const f32x2 v = {lo, hi}; return __builtin_bit_cast(unsigned, __builtin_convertvector(v, bf16x2_t)); }
; template <int MODE> __device__ __forceinline__ void ssd_scan_phase(Frame& F, int j, bool ctx_out) {
;     ...
;             if (!(MODE & 8)) SCAN_DMA(BS, btp, T);
;             if (need_y && !(MODE & 1)) {
;                 bf16x8 hf[2][4];
; #pragma unroll
;                 for (int pt = 0; pt < 2; ++pt)
; #pragma unroll
;                     for (int q = 0; q < 4; ++q) { const f32x4 lo4 = hT[2 * q][pt], hi4 = hT[2 * q + 1][pt]; u32x4 o; o.x = cvt_pk_bf16(lo4[0], lo4[1]); o.y = cvt_pk_bf16(lo4[2], lo4[3]); o.z = cvt_pk_bf16(hi4[0], hi4[1]); o.w = cvt_pk_bf16(hi4[2], hi4[3]);
;                         hf[pt][q] = __builtin_bit_cast(bf16x8, o); }
;                 bf16x8 xb_cur = xf[1][0], xb_nxt = xf[1][0];
; #pragma unroll 8
;                 for (int lt = 0; lt < 8; ++lt) {
;                     const int l = 16 * lt + fr; const float cl = tab[l];
;                     f32x4 accd[2], acco[2];
;                     accd[0] = accd[1] = acco[0] = acco[1] = (f32x4){0.f, 0.f, 0.f, 0.f};
;                     const int kd = lt >> 1;
;                     if ((lt & 1) == 0) { xb_cur = xb_nxt; if (kd + 1 < 4) xb_nxt = *(const bf16x8*)(xl + (size_t)16 * T + 32 * (kd + 1)); }
;                     const bf16x8 xa = xf[0][kd], xb = xb_cur;
; #pragma unroll
;                     for (int ks = 0; ks < 4; ++ks) {
;                         const bool full = dir == 0 ? (ks < kd) : (ks > kd);
;                         if (full) {
;                             const bf16x8 gf = *(const LAS bf16x8*)(GS + l * 256 + (((4 * ks + fq) ^ fr) << 4));
;                             const float f1 = __builtin_amdgcn_exp2f(cl - tab[dir == 0 ? 32 * ks + 31 : 32 * ks]);
;                             const f32x4 z4 = (f32x4){0.f, 0.f, 0.f, 0.f};
;                             const f32x4 t0 = __builtin_amdgcn_mfma_f32_16x16x32_bf16(xs2[0][ks], gf, z4, 0, 0, 0), t1 = __builtin_amdgcn_mfma_f32_16x16x32_bf16(xs2[1][ks], gf, z4, 0, 0, 0);
;                             accd[0] += t0 * f1; accd[1] += t1 * f1;
	global_load_lds_dwordx4 v[104:105], off nt
	v_add_u32_e32 v104, 0x200, v106
	v_ashrrev_i32_e32 v192, 4, v104
	v_xor_b32_e32 v107, v192, v209
	v_lshlrev_b32_e32 v107, 3, v107
	v_mad_i64_i32 v[104:105], s[48:49], s42, v192, 0
	v_and_b32_e32 v107, 0x78, v107
	v_lshl_add_u64 v[104:105], v[104:105], 1, s[46:47]
	v_lshlrev_b32_e32 v184, 1, v107
	v_mov_b32_e32 v185, v177
	v_lshl_add_u64 v[104:105], v[104:105], 0, v[184:185]
	s_add_i32 m0, s17, 0x2000
	v_mov_b32_e32 v187, v177
	global_load_lds_dwordx4 v[104:105], off nt
	v_add_u32_e32 v104, 0x400, v106
	v_ashrrev_i32_e32 v194, 4, v104
	v_xor_b32_e32 v107, v194, v209
	v_lshlrev_b32_e32 v107, 3, v107
	v_mad_i64_i32 v[104:105], s[48:49], s42, v194, 0
	v_and_b32_e32 v107, 0x78, v107
	v_lshl_add_u64 v[104:105], v[104:105], 1, s[46:47]
	v_lshlrev_b32_e32 v186, 1, v107
	v_lshl_add_u64 v[104:105], v[104:105], 0, v[186:187]
	s_add_i32 m0, s17, 0x4000
	v_mov_b32_e32 v191, v177
	global_load_lds_dwordx4 v[104:105], off nt
	v_add_u32_e32 v104, 0x600, v106
	v_ashrrev_i32_e32 v196, 4, v104
	v_xor_b32_e32 v106, v196, v209
	v_lshlrev_b32_e32 v106, 3, v106
	v_mad_i64_i32 v[104:105], s[48:49], s42, v196, 0
	v_and_b32_e32 v106, 0x78, v106
	v_lshl_add_u64 v[104:105], v[104:105], 1, s[46:47]
	v_lshlrev_b32_e32 v190, 1, v106
	v_lshl_add_u64 v[104:105], v[104:105], 0, v[190:191]
	s_add_i32 m0, s17, 0x6000
	v_pk_mul_f32 v[108:109], v[108:109], v[112:113]
	global_load_lds_dwordx4 v[104:105], off nt
	v_cvt_pk_bf16_f32 v87, v122, v123
	v_cvt_pk_bf16_f32 v82, v82, v83
	v_cvt_pk_bf16_f32 v83, v120, v121
	v_cvt_pk_bf16_f32 v51, v114, v115
	v_cvt_pk_bf16_f32 v44, v108, v109
	v_cvt_pk_bf16_f32 v45, v110, v111
	s_andn2_b64 vcc, exec, s[40:41]
	s_cbranch_vccnz .LBB0_523
	s_lshl_b32 s40, s43, 7
	s_lshl_b32 s17, s40, 1
	v_mul_u32_u24_e32 v104, s42, v176
	s_add_u32 s44, s44, s17
	s_addc_u32 s45, s45, 0
	v_lshlrev_b32_e32 v104, 1, v104
	v_mov_b32_e32 v105, v177
	v_lshl_add_u64 v[104:105], s[44:45], 0, v[104:105]
	v_lshl_add_u64 v[104:105], v[180:181], 1, v[104:105]
	s_lshl_b32 s42, s42, 5
	s_mov_b32 s43, s92
	v_lshl_add_u64 v[200:201], v[104:105], 0, s[42:43]
	global_load_dwordx4 v[148:151], v[200:201], off offset:64 nt
	v_lshl_add_u32 v214, v176, 2, s18
	ds_read_b32 v216, v214
	v_cndmask_b32_e64 v104, 0, 1, s[36:37]
	v_cmp_ne_u32_e64 s[44:45], 1, v104
	s_andn2_b64 vcc, exec, s[36:37]
	v_add_u32_e32 v166, s87, v132
	s_cbranch_vccnz .LBB0_490
	v_mov_b32_e32 v108, s18
	v_lshl_add_u32 v104, v207, 4, v166
	ds_read_b32 v112, v108 offset:128
	ds_read_b128 v[104:107], v104
	s_waitcnt lgkmcnt(0)
	v_mfma_f32_16x16x32_bf16 v[108:111], v[84:87], v[104:107], 0
	v_sub_f32_e32 v112, v216, v112
	v_exp_f32_e32 v112, v112
	v_mfma_f32_16x16x32_bf16 v[104:107], v[88:91], v[104:107], 0
	s_nop 4
	v_fma_f32 v156, v108, v112, 0
	v_fma_f32 v157, v109, v112, 0
	v_pk_fma_f32 v[158:159], v[110:111], v[112:113], 0 op_sel_hi:[1,0,0]
	v_pk_fma_f32 v[152:153], v[104:105], v[112:113], 0 op_sel_hi:[1,0,0]
	v_pk_fma_f32 v[154:155], v[106:107], v[112:113], 0 op_sel_hi:[1,0,0]
	s_and_b64 vcc, exec, s[44:45]
	s_cbranch_vccz .LBB0_491
	s_branch .LBB0_492

; #define LAS __attribute__((address_space(3)))
; template <int MODE> __device__ __forceinline__ void ssd_scan_phase(Frame& F, int j, bool ctx_out) {
;     ...
; #pragma unroll
;                     for (int q = 0; q < 4; ++q) {
;                         const u32x2 lo = *(const LAS u32x2*)(CS + l * 256 + (((4 * q + (fq >> 1)) ^ fr) << 4) + (fq & 1) * 8), hi = *(const LAS u32x2*)(CS + l * 256 + (((4 * q + 2 + (fq >> 1)) ^ fr) << 4) + (fq & 1) * 8);
;                         u32x4 c4; c4.x = lo.x; c4.y = lo.y; c4.z = hi.x; c4.w = hi.y; const bf16x8 cfr = __builtin_bit_cast(bf16x8, c4);
;                         acco[0] = __builtin_amdgcn_mfma_f32_16x16x32_bf16(hf[0][q], cfr, acco[0], 0, 0, 0);
;                         acco[1] = __builtin_amdgcn_mfma_f32_16x16x32_bf16(hf[1][q], cfr, acco[1], 0, 0, 0);
.LBB0_498:
	v_add3_u32 v178, 0, v226, v195
	v_add_u32_e32 v179, v178, v185
	ds_read_b64 v[226:227], v179
	v_add_u32_e32 v179, v178, v183
	ds_read_b64 v[228:229], v179
	v_add_u32_e32 v179, v178, v187
	ds_read_b64 v[234:235], v179
	v_add_u32_e32 v179, v178, v213
	ds_read_b64 v[236:237], v179
	s_waitcnt lgkmcnt(0)
	v_mfma_f32_16x16x32_bf16 v[230:233], v[116:119], v[226:229], 0
	v_add_u32_e32 v179, v178, v212
	ds_read_b64 v[246:247], v179
	v_add_u32_e32 v179, v178, v211
	v_mfma_f32_16x16x32_bf16 v[226:229], v[124:127], v[226:229], 0
	ds_read_b64 v[248:249], v179
	v_add_u32_e32 v179, v178, v191
	v_add_u32_e32 v178, v178, v210
	v_mfma_f32_16x16x32_bf16 v[230:233], v[112:115], v[234:237], v[230:233]
	v_cmp_le_i32_e32 vcc, v180, v216
	v_cmp_ge_i32_e64 s[46:47], v180, v216
	v_sub_f32_e32 v172, v217, v172
	v_mfma_f32_16x16x32_bf16 v[226:229], v[120:123], v[234:237], v[226:229]
	ds_read_b64 v[234:235], v179
	v_add_u32_e32 v179, v225, v215
	v_exp_f32_e32 v172, v172
	s_waitcnt lgkmcnt(0)
	v_mfma_f32_16x16x32_bf16 v[230:233], v[108:111], v[246:249], v[230:233]
	v_sub_f32_e32 v173, v217, v173
	v_exp_f32_e32 v173, v173
	v_sub_f32_e32 v174, v217, v174
	v_mfma_f32_16x16x32_bf16 v[226:229], v[128:131], v[246:249], v[226:229]
	ds_read_b128 v[246:249], v179
	ds_read_b64 v[236:237], v178
	v_exp_f32_e32 v174, v174
	v_sub_f32_e32 v164, v217, v164
	v_exp_f32_e32 v164, v164
	s_waitcnt lgkmcnt(0)
; #define LAS __attribute__((address_space(3)))
; __device__ __forceinline__ unsigned cvt_pk_bf16(float lo, float hi) { const f32x2 v = {lo, hi}; return __builtin_bit_cast(unsigned, __builtin_convertvector(v, bf16x2_t)); }
; __device__ __forceinline__ u32x4 pack8(const float (&f)[8]) { u32x4 w; w.x = cvt_pk_bf16(f[0], f[1]); w.y = cvt_pk_bf16(f[2], f[3]); w.z = cvt_pk_bf16(f[4], f[5]); w.w = cvt_pk_bf16(f[6], f[7]); return w; }
; template <int MODE> __device__ __forceinline__ void ssd_scan_phase(Frame& F, int j, bool ctx_out) {
;     ...
;                     if ((lt & 1) == 0) { xb_cur = xb_nxt; if (kd + 1 < 4) xb_nxt = *(const bf16x8*)(xl + (size_t)16 * T + 32 * (kd + 1)); }
;     ...
;                     {
;                         float gg[8]; unpack8(*(const LAS u32x4*)(GS + l * 256 + (((4 * kd + fq) ^ fr) << 4)), gg);
;                         const f32x4 ca = *(const LAS f32x4*)(tab + 32 * kd + 8 * fq), cb = *(const LAS f32x4*)(tab + 32 * kd + 8 * fq + 4);
;                         const f32x4 da = *(const LAS f32x4*)(tab + 128 + 32 * kd + 8 * fq), db = *(const LAS f32x4*)(tab + 128 + 32 * kd + 8 * fq + 4);
;                         const float cs[8] = {ca.x, ca.y, ca.z, ca.w, cb.x, cb.y, cb.z, cb.w}, ds[8] = {da.x, da.y, da.z, da.w, db.x, db.y, db.z, db.w};
;                         float m[8];
; #pragma unroll
;                         for (int jj = 0; jj < 8; ++jj) { const int s = 32 * kd + 8 * fq + jj; const bool valid = dir == 0 ? (s <= l) : (s >= l);
;                             const float e = valid ? __builtin_amdgcn_exp2f(cl - cs[jj]) : 0.f; m[jj] = gg[jj] * e * ds[jj]; if (dir == 0 && s == l) m[jj] += dsk; }
;                         const bf16x8 mf = __builtin_bit_cast(bf16x8, pack8(m));
;                         accd[0] = __builtin_amdgcn_mfma_f32_16x16x32_bf16(xa, mf, accd[0], 0, 0, 0);
;                         accd[1] = __builtin_amdgcn_mfma_f32_16x16x32_bf16(xb, mf, accd[1], 0, 0, 0);
;                     }
;                     const float el = __builtin_amdgcn_exp2f(cl);
; #pragma unroll
;                     for (int pt = 0; pt < 2; ++pt) { const f32x4 y = accd[pt] + acco[pt] * el; u32x2 o; o.x = cvt_pk_bf16(y[0], y[1]); o.y = cvt_pk_bf16(y[2], y[3]);
;                         *(u32x2*)(yout + (size_t)(row0 + l) * DI + h * 64 + ph * 32 + 16 * pt + 4 * fq) = o; }
	v_lshlrev_b32_e32 v178, 16, v246
	v_and_b32_e32 v179, 0xffff0000, v246
	v_lshlrev_b32_e32 v225, 16, v247
	v_and_b32_e32 v240, 0xffff0000, v247
	v_cndmask_b32_e64 v246, 0, 1, vcc
	v_cndmask_b32_e64 v247, 0, 1, s[46:47]
	v_cndmask_b32_e64 v246, v247, v246, s[38:39]
	v_and_b32_e32 v246, 1, v246
	v_cmp_eq_u32_e32 vcc, 1, v246
	v_cmp_ge_i32_e64 s[46:47], v218, v216
	v_mfma_f32_16x16x32_bf16 v[230:233], v[104:107], v[234:237], v[230:233]
	v_cndmask_b32_e32 v172, 0, v172, vcc
	v_mul_f32_e32 v172, v172, v178
	v_cmp_eq_u32_e32 vcc, v180, v216
	v_mul_f32_e32 v178, v168, v172
	s_and_b64 vcc, s[38:39], vcc
	v_fma_f32 v168, v168, v172, v203
	v_cndmask_b32_e32 v168, v178, v168, vcc
	v_cmp_lt_i32_e32 vcc, v180, v216
	v_cndmask_b32_e64 v172, 0, 1, s[46:47]
	v_cmp_ge_i32_e64 s[46:47], v219, v216
	v_cndmask_b32_e64 v178, 0, 1, vcc
	v_cndmask_b32_e64 v172, v172, v178, s[38:39]
	v_and_b32_e32 v172, 1, v172
	v_cmp_eq_u32_e32 vcc, 1, v172
	v_mfma_f32_16x16x32_bf16 v[226:229], v[132:135], v[234:237], v[226:229]
	v_lshlrev_b32_e32 v234, 16, v248
	v_cndmask_b32_e32 v172, 0, v173, vcc
	v_mul_f32_e32 v172, v172, v179
	v_cmp_eq_u32_e32 vcc, v218, v216
	v_mul_f32_e32 v173, v169, v172
	s_and_b64 vcc, s[38:39], vcc
	v_fma_f32 v169, v169, v172, v203
	v_cndmask_b32_e32 v169, v173, v169, vcc
	v_cmp_le_i32_e32 vcc, v219, v216
	v_cndmask_b32_e64 v173, 0, 1, s[46:47]
	v_cmp_ge_i32_e64 s[46:47], v220, v216
	v_cndmask_b32_e64 v172, 0, 1, vcc
	v_cndmask_b32_e64 v172, v173, v172, s[38:39]
	v_and_b32_e32 v172, 1, v172
	v_cmp_eq_u32_e32 vcc, 1, v172
	v_sub_f32_e32 v165, v217, v165
	v_exp_f32_e32 v165, v165
	v_cndmask_b32_e32 v172, 0, v174, vcc
	v_mul_f32_e32 v172, v172, v225
	v_cmp_eq_u32_e32 vcc, v219, v216
	v_mul_f32_e32 v173, v170, v172
	s_and_b64 vcc, s[38:39], vcc
	v_fma_f32 v170, v170, v172, v203
	v_cndmask_b32_e32 v170, v173, v170, vcc
	v_cmp_le_i32_e32 vcc, v220, v216
	v_sub_f32_e32 v174, v217, v175
	v_cndmask_b32_e64 v173, 0, 1, s[46:47]
	v_cndmask_b32_e64 v172, 0, 1, vcc
	v_exp_f32_e32 v174, v174
	v_cndmask_b32_e64 v172, v173, v172, s[38:39]
	v_and_b32_e32 v172, 1, v172
	v_cmp_eq_u32_e32 vcc, 1, v172
	v_cmp_ge_i32_e64 s[46:47], v221, v216
	v_and_b32_e32 v235, 0xffff0000, v248
	v_cndmask_b32_e32 v172, 0, v174, vcc
	v_mul_f32_e32 v172, v172, v240
	v_cmp_eq_u32_e32 vcc, v220, v216
	v_mul_f32_e32 v173, v171, v172
	s_and_b64 vcc, s[38:39], vcc
	v_fma_f32 v171, v171, v172, v203
	v_cndmask_b32_e32 v171, v173, v171, vcc
	v_cmp_le_i32_e32 vcc, v221, v216
	v_cndmask_b32_e64 v173, 0, 1, s[46:47]
	v_cmp_ge_i32_e64 s[46:47], v222, v216
	v_cndmask_b32_e64 v172, 0, 1, vcc
	v_cndmask_b32_e64 v172, v173, v172, s[38:39]
	v_and_b32_e32 v172, 1, v172
	v_cmp_eq_u32_e32 vcc, 1, v172
	v_sub_f32_e32 v166, v217, v166
	v_exp_f32_e32 v166, v166
	v_cndmask_b32_e32 v164, 0, v164, vcc
	v_mul_f32_e32 v164, v164, v234
	v_cmp_eq_u32_e32 vcc, v221, v216
	v_mul_f32_e32 v172, v160, v164
	s_and_b64 vcc, s[38:39], vcc
	v_fma_f32 v160, v160, v164, v203
	v_cndmask_b32_e32 v164, v172, v160, vcc
	v_cmp_le_i32_e32 vcc, v222, v216
	v_cndmask_b32_e64 v172, 0, 1, s[46:47]
	v_cmp_ge_i32_e64 s[46:47], v223, v216
	v_cndmask_b32_e64 v160, 0, 1, vcc
	v_cndmask_b32_e64 v160, v172, v160, s[38:39]
	v_and_b32_e32 v160, 1, v160
	v_cmp_eq_u32_e32 vcc, 1, v160
	v_lshlrev_b32_e32 v236, 16, v249
	v_and_b32_e32 v237, 0xffff0000, v249
	v_cndmask_b32_e32 v160, 0, v165, vcc
	v_mul_f32_e32 v160, v160, v235
	v_cmp_eq_u32_e32 vcc, v222, v216
	v_mul_f32_e32 v165, v161, v160
	s_and_b64 vcc, s[38:39], vcc
	v_fma_f32 v160, v161, v160, v203
	v_cndmask_b32_e32 v165, v165, v160, vcc
	v_cmp_le_i32_e32 vcc, v223, v216
	v_cndmask_b32_e64 v161, 0, 1, s[46:47]
	v_cmp_ge_i32_e64 s[46:47], v224, v216
	v_cndmask_b32_e64 v160, 0, 1, vcc
	v_cndmask_b32_e64 v160, v161, v160, s[38:39]
	v_and_b32_e32 v160, 1, v160
	v_cmp_eq_u32_e32 vcc, 1, v160
	ds_read_b32 v174, v214 offset:128
	s_mov_b32 s94, s92
	v_cndmask_b32_e32 v160, 0, v166, vcc
	v_mul_f32_e32 v160, v160, v236
	v_cmp_eq_u32_e32 vcc, v223, v216
	v_mul_f32_e32 v161, v162, v160
	s_and_b64 vcc, s[38:39], vcc
	v_fma_f32 v160, v162, v160, v203
	v_cndmask_b32_e32 v166, v161, v160, vcc
	v_cmp_le_i32_e32 vcc, v224, v216
	v_sub_f32_e32 v162, v217, v167
	v_cndmask_b32_e64 v161, 0, 1, s[46:47]
	v_cndmask_b32_e64 v160, 0, 1, vcc
	v_exp_f32_e32 v162, v162
	v_cndmask_b32_e64 v160, v161, v160, s[38:39]
	v_and_b32_e32 v160, 1, v160
	v_cmp_eq_u32_e32 vcc, 1, v160
	s_mov_b32 s95, s92
	v_or_b32_e32 v173, 32, v176
	v_cndmask_b32_e32 v160, 0, v162, vcc
	v_mul_f32_e32 v160, v160, v237
	v_cmp_eq_u32_e32 vcc, v224, v216
	v_mul_f32_e32 v161, v163, v160
	s_and_b64 vcc, s[38:39], vcc
	v_fma_f32 v160, v163, v160, v203
	v_cndmask_b32_e32 v163, v161, v160, vcc
	v_cvt_pk_bf16_f32 v160, v168, v169
	v_cvt_pk_bf16_f32 v161, v170, v171
	v_cvt_pk_bf16_f32 v162, v164, v165
	v_cvt_pk_bf16_f32 v163, v166, v163
	s_mov_b32 s93, s92
	s_andn2_b64 vcc, exec, s[38:39]
	v_mfma_f32_16x16x32_bf16 v[140:143], v[140:143], v[160:163], v[152:155]
	s_nop 2
	v_exp_f32_e32 v152, v217
	v_mfma_f32_16x16x32_bf16 v[144:147], v[144:147], v[160:163], v[156:159]
	v_add_u32_e32 v154, s5, v216
	v_ashrrev_i32_e32 v155, 31, v154
	v_lshlrev_b64 v[154:155], 13, v[154:155]
	v_pk_fma_f32 v[142:143], v[152:153], v[232:233], v[142:143] op_sel_hi:[0,1,1]
	v_pk_fma_f32 v[140:141], v[152:153], v[230:231], v[140:141] op_sel_hi:[0,1,1]
	v_lshl_add_u64 v[154:155], v[198:199], 0, v[154:155]
	v_cvt_pk_bf16_f32 v140, v140, v141
	v_cvt_pk_bf16_f32 v141, v142, v143
	global_store_dwordx2 v[154:155], v[140:141], off
	v_pk_fma_f32 v[140:141], v[152:153], v[228:229], v[146:147] op_sel_hi:[0,1,1]
	v_pk_fma_f32 v[142:143], v[152:153], v[226:227], v[144:145] op_sel_hi:[0,1,1]
	v_cvt_pk_bf16_f32 v142, v142, v143
	v_cvt_pk_bf16_f32 v143, v140, v141
	global_store_dwordx2 v[154:155], v[142:143], off offset:32
	global_load_dwordx4 v[140:143], v[200:201], off offset:128 nt
	v_cndmask_b32_e64 v152, 0, 1, s[38:39]
	v_mov_b64_e32 v[146:147], s[94:95]
	v_lshlrev_b32_e32 v156, 8, v173
	v_cmp_ne_u32_e64 s[46:47], 1, v152
	v_mov_b64_e32 v[154:155], s[94:95]
	v_mov_b64_e32 v[144:145], s[92:93]
	v_add_u32_e32 v160, s87, v156
	v_mov_b64_e32 v[152:153], s[92:93]
	s_cbranch_vccz .LBB0_528
	s_and_b64 vcc, exec, s[44:45]
	s_cbranch_vccz .LBB0_529

; #define LAS __attribute__((address_space(3)))
; template <int MODE> __device__ __forceinline__ void ssd_scan_phase(Frame& F, int j, bool ctx_out) {
;     ...
; #pragma unroll
;                     for (int q = 0; q < 4; ++q) {
;                         const u32x2 lo = *(const LAS u32x2*)(CS + l * 256 + (((4 * q + (fq >> 1)) ^ fr) << 4) + (fq & 1) * 8), hi = *(const LAS u32x2*)(CS + l * 256 + (((4 * q + 2 + (fq >> 1)) ^ fr) << 4) + (fq & 1) * 8);
;                         u32x4 c4; c4.x = lo.x; c4.y = lo.y; c4.z = hi.x; c4.w = hi.y; const bf16x8 cfr = __builtin_bit_cast(bf16x8, c4);
;                         acco[0] = __builtin_amdgcn_mfma_f32_16x16x32_bf16(hf[0][q], cfr, acco[0], 0, 0, 0);
;                         acco[1] = __builtin_amdgcn_mfma_f32_16x16x32_bf16(hf[1][q], cfr, acco[1], 0, 0, 0);
;                     }
;                     {
;                         float gg[8]; unpack8(*(const LAS u32x4*)(GS + l * 256 + (((4 * kd + fq) ^ fr) << 4)), gg);
;                         const f32x4 ca = *(const LAS f32x4*)(tab + 32 * kd + 8 * fq), cb = *(const LAS f32x4*)(tab + 32 * kd + 8 * fq + 4);
;                         const f32x4 da = *(const LAS f32x4*)(tab + 128 + 32 * kd + 8 * fq), db = *(const LAS f32x4*)(tab + 128 + 32 * kd + 8 * fq + 4);
;                         const float cs[8] = {ca.x, ca.y, ca.z, ca.w, cb.x, cb.y, cb.z, cb.w}, ds[8] = {da.x, da.y, da.z, da.w, db.x, db.y, db.z, db.w};
;                         float m[8];
; #pragma unroll
;                         for (int jj = 0; jj < 8; ++jj) { const int s = 32 * kd + 8 * fq + jj; const bool valid = dir == 0 ? (s <= l) : (s >= l);
;                             const float e = valid ? __builtin_amdgcn_exp2f(cl - cs[jj]) : 0.f; m[jj] = gg[jj] * e * ds[jj]; if (dir == 0 && s == l) m[jj] += dsk; }
.LBB0_506:
	v_add3_u32 v178, 0, v223, v195
	v_add_u32_e32 v179, v178, v185
	ds_read_b64 v[224:225], v179
	v_add_u32_e32 v179, v178, v183
	ds_read_b64 v[226:227], v179
	v_add_u32_e32 v179, v178, v187
	ds_read_b64 v[232:233], v179
	v_add_u32_e32 v179, v178, v213
	ds_read_b64 v[234:235], v179
	s_waitcnt lgkmcnt(2)
	v_mfma_f32_16x16x32_bf16 v[228:231], v[116:119], v[224:227], 0
	v_add_u32_e32 v179, v178, v212
	ds_read_b64 v[246:247], v179
	v_add_u32_e32 v179, v178, v211
	v_mfma_f32_16x16x32_bf16 v[224:227], v[124:127], v[224:227], 0
	ds_read_b64 v[248:249], v179
	v_add_u32_e32 v174, v174, v172
	v_sub_f32_e32 v168, v175, v168
	s_waitcnt lgkmcnt(2)
	v_mfma_f32_16x16x32_bf16 v[228:231], v[112:115], v[232:235], v[228:231]
	v_exp_f32_e32 v168, v168
	v_add_u32_e32 v179, v178, v191
	v_add_u32_e32 v178, v178, v210
	v_mfma_f32_16x16x32_bf16 v[224:227], v[120:123], v[232:235], v[224:227]
	ds_read_b64 v[232:233], v179
	ds_read_b64 v[234:235], v178
	v_sub_f32_e32 v169, v175, v169
	s_waitcnt lgkmcnt(2)
	v_mfma_f32_16x16x32_bf16 v[228:231], v[108:111], v[246:249], v[228:231]
	v_exp_f32_e32 v169, v169
	v_sub_f32_e32 v170, v175, v170
	v_exp_f32_e32 v170, v170
	v_mfma_f32_16x16x32_bf16 v[224:227], v[128:131], v[246:249], v[224:227]
	ds_read_b128 v[246:249], v174
	v_add_u32_e32 v174, 32, v180
	v_cmp_le_i32_e32 vcc, v174, v173
	v_cmp_ge_i32_e64 s[48:49], v174, v173
	s_waitcnt lgkmcnt(1)
	v_mfma_f32_16x16x32_bf16 v[228:231], v[104:107], v[232:235], v[228:231]
	v_cndmask_b32_e64 v237, 0, 1, vcc
	v_cndmask_b32_e64 v240, 0, 1, s[48:49]
	v_cndmask_b32_e64 v237, v240, v237, s[38:39]
	v_and_b32_e32 v237, 1, v237
	v_cmp_eq_u32_e32 vcc, 1, v237
	s_waitcnt lgkmcnt(0)
; template <int MODE> __device__ __forceinline__ void ssd_scan_phase(Frame& F, int j, bool ctx_out) {
;     ...
;                     if ((lt & 1) == 0) { xb_cur = xb_nxt; if (kd + 1 < 4) xb_nxt = *(const bf16x8*)(xl + (size_t)16 * T + 32 * (kd + 1)); }
;                     const bf16x8 xa = xf[0][kd], xb = xb_cur;
; #pragma unroll
;                     for (int ks = 0; ks < 4; ++ks) {
;                         const bool full = dir == 0 ? (ks < kd) : (ks > kd);
;                         if (full) {
;                             const bf16x8 gf = *(const LAS bf16x8*)(GS + l * 256 + (((4 * ks + fq) ^ fr) << 4));
;                             const float f1 = __builtin_amdgcn_exp2f(cl - tab[dir == 0 ? 32 * ks + 31 : 32 * ks]);
;                             const f32x4 z4 = (f32x4){0.f, 0.f, 0.f, 0.f};
;                             const f32x4 t0 = __builtin_amdgcn_mfma_f32_16x16x32_bf16(xs2[0][ks], gf, z4, 0, 0, 0), t1 = __builtin_amdgcn_mfma_f32_16x16x32_bf16(xs2[1][ks], gf, z4, 0, 0, 0);
;                             accd[0] += t0 * f1; accd[1] += t1 * f1;
;                         }
;                     }
; #pragma unroll
;                     for (int q = 0; q < 4; ++q) {
;                         const u32x2 lo = *(const LAS u32x2*)(CS + l * 256 + (((4 * q + (fq >> 1)) ^ fr) << 4) + (fq & 1) * 8), hi = *(const LAS u32x2*)(CS + l * 256 + (((4 * q + 2 + (fq >> 1)) ^ fr) << 4) + (fq & 1) * 8);
;                         u32x4 c4; c4.x = lo.x; c4.y = lo.y; c4.z = hi.x; c4.w = hi.y; const bf16x8 cfr = __builtin_bit_cast(bf16x8, c4);
;                         acco[0] = __builtin_amdgcn_mfma_f32_16x16x32_bf16(hf[0][q], cfr, acco[0], 0, 0, 0);
;                         acco[1] = __builtin_amdgcn_mfma_f32_16x16x32_bf16(hf[1][q], cfr, acco[1], 0, 0, 0);
;                     }
;                     {
;                         float gg[8]; unpack8(*(const LAS u32x4*)(GS + l * 256 + (((4 * kd + fq) ^ fr) << 4)), gg);
;                         const f32x4 ca = *(const LAS f32x4*)(tab + 32 * kd + 8 * fq), cb = *(const LAS f32x4*)(tab + 32 * kd + 8 * fq + 4);
;                         const f32x4 da = *(const LAS f32x4*)(tab + 128 + 32 * kd + 8 * fq), db = *(const LAS f32x4*)(tab + 128 + 32 * kd + 8 * fq + 4);
;                         const float cs[8] = {ca.x, ca.y, ca.z, ca.w, cb.x, cb.y, cb.z, cb.w}, ds[8] = {da.x, da.y, da.z, da.w, db.x, db.y, db.z, db.w};
	v_lshlrev_b32_e32 v178, 16, v246
	v_cmp_ge_i32_e64 s[48:49], v216, v173
	v_cndmask_b32_e32 v168, 0, v168, vcc
	v_mul_f32_e32 v168, v168, v178
	v_cmp_eq_u32_e32 vcc, v174, v173
	v_mul_f32_e32 v178, v164, v168
	s_and_b64 vcc, s[38:39], vcc
	v_fma_f32 v164, v164, v168, v203
	v_cndmask_b32_e32 v164, v178, v164, vcc
	v_cmp_le_i32_e32 vcc, v216, v173
	v_cndmask_b32_e64 v174, 0, 1, s[48:49]
	v_and_b32_e32 v179, 0xffff0000, v246
	v_cndmask_b32_e64 v168, 0, 1, vcc
	v_cndmask_b32_e64 v168, v174, v168, s[38:39]
	v_and_b32_e32 v168, 1, v168
	v_cmp_eq_u32_e32 vcc, 1, v168
	v_cmp_ge_i32_e64 s[48:49], v217, v173
	v_lshlrev_b32_e32 v223, 16, v247
	v_cndmask_b32_e32 v168, 0, v169, vcc
	v_mul_f32_e32 v168, v168, v179
	v_cmp_eq_u32_e32 vcc, v216, v173
	v_mul_f32_e32 v169, v165, v168
	s_and_b64 vcc, s[38:39], vcc
	v_fma_f32 v165, v165, v168, v203
	v_cndmask_b32_e32 v165, v169, v165, vcc
	v_cmp_le_i32_e32 vcc, v217, v173
	v_cndmask_b32_e64 v169, 0, 1, s[48:49]
	v_cmp_ge_i32_e64 s[48:49], v218, v173
	v_cndmask_b32_e64 v168, 0, 1, vcc
	v_cndmask_b32_e64 v168, v169, v168, s[38:39]
	v_and_b32_e32 v168, 1, v168
	v_cmp_eq_u32_e32 vcc, 1, v168
	v_mfma_f32_16x16x32_bf16 v[224:227], v[132:135], v[232:235], v[224:227]
	v_and_b32_e32 v232, 0xffff0000, v247
	v_cndmask_b32_e32 v168, 0, v170, vcc
	v_mul_f32_e32 v168, v168, v223
	v_cmp_eq_u32_e32 vcc, v217, v173
	v_mul_f32_e32 v169, v166, v168
	s_and_b64 vcc, s[38:39], vcc
	v_fma_f32 v166, v166, v168, v203
	v_cndmask_b32_e32 v166, v169, v166, vcc
	v_cmp_le_i32_e32 vcc, v218, v173
	v_sub_f32_e32 v170, v175, v171
	v_cndmask_b32_e64 v169, 0, 1, s[48:49]
	v_cndmask_b32_e64 v168, 0, 1, vcc
	v_exp_f32_e32 v170, v170
	v_cndmask_b32_e64 v168, v169, v168, s[38:39]
	v_and_b32_e32 v168, 1, v168
	v_cmp_eq_u32_e32 vcc, 1, v168
	v_cmp_ge_i32_e64 s[48:49], v219, v173
	v_sub_f32_e32 v160, v175, v160
	v_cndmask_b32_e32 v168, 0, v170, vcc
	v_mul_f32_e32 v168, v168, v232
	v_cmp_eq_u32_e32 vcc, v218, v173
	v_mul_f32_e32 v169, v167, v168
	s_and_b64 vcc, s[38:39], vcc
	v_fma_f32 v167, v167, v168, v203
	v_cndmask_b32_e32 v167, v169, v167, vcc
	v_cmp_le_i32_e32 vcc, v219, v173
	v_cndmask_b32_e64 v169, 0, 1, s[48:49]
	v_exp_f32_e32 v160, v160
	v_cndmask_b32_e64 v168, 0, 1, vcc
	v_cndmask_b32_e64 v168, v169, v168, s[38:39]
	v_and_b32_e32 v168, 1, v168
	v_cmp_eq_u32_e32 vcc, 1, v168
	v_lshlrev_b32_e32 v233, 16, v248
	v_cmp_ge_i32_e64 s[48:49], v220, v173
	v_cndmask_b32_e32 v160, 0, v160, vcc
	v_mul_f32_e32 v160, v160, v233
	v_cmp_eq_u32_e32 vcc, v219, v173
	v_mul_f32_e32 v168, v156, v160
	s_and_b64 vcc, s[38:39], vcc
	v_fma_f32 v156, v156, v160, v203
	v_cndmask_b32_e32 v160, v168, v156, vcc
	v_cmp_le_i32_e32 vcc, v220, v173
	v_sub_f32_e32 v161, v175, v161
	v_cndmask_b32_e64 v168, 0, 1, s[48:49]
	v_cndmask_b32_e64 v156, 0, 1, vcc
	v_exp_f32_e32 v161, v161
	v_cndmask_b32_e64 v156, v168, v156, s[38:39]
	v_and_b32_e32 v156, 1, v156
	v_cmp_eq_u32_e32 vcc, 1, v156
	v_and_b32_e32 v234, 0xffff0000, v248
	v_cmp_ge_i32_e64 s[48:49], v221, v173
	v_cndmask_b32_e32 v156, 0, v161, vcc
	v_mul_f32_e32 v156, v156, v234
	v_cmp_eq_u32_e32 vcc, v220, v173
	v_mul_f32_e32 v161, v157, v156
	s_and_b64 vcc, s[38:39], vcc
	v_fma_f32 v156, v157, v156, v203
	v_cndmask_b32_e32 v161, v161, v156, vcc
	v_cmp_le_i32_e32 vcc, v221, v173
	v_sub_f32_e32 v162, v175, v162
	v_cndmask_b32_e64 v157, 0, 1, s[48:49]
	v_cndmask_b32_e64 v156, 0, 1, vcc
	v_exp_f32_e32 v162, v162
	v_cndmask_b32_e64 v156, v157, v156, s[38:39]
	v_and_b32_e32 v156, 1, v156
	v_cmp_eq_u32_e32 vcc, 1, v156
	v_lshlrev_b32_e32 v235, 16, v249
	v_cmp_ge_i32_e64 s[48:49], v222, v173
	v_cndmask_b32_e32 v156, 0, v162, vcc
	v_mul_f32_e32 v156, v156, v235
	v_cmp_eq_u32_e32 vcc, v221, v173
	v_mul_f32_e32 v157, v158, v156
	s_and_b64 vcc, s[38:39], vcc
	v_fma_f32 v156, v158, v156, v203
	v_cndmask_b32_e32 v162, v157, v156, vcc
	v_cmp_le_i32_e32 vcc, v222, v173
	v_sub_f32_e32 v158, v175, v163
	v_cndmask_b32_e64 v157, 0, 1, s[48:49]
	v_cndmask_b32_e64 v156, 0, 1, vcc
	v_exp_f32_e32 v158, v158
	v_cndmask_b32_e64 v156, v157, v156, s[38:39]
	v_and_b32_e32 v156, 1, v156
	v_cmp_eq_u32_e32 vcc, 1, v156
	v_and_b32_e32 v236, 0xffff0000, v249
	ds_read_b32 v170, v214 offset:256
	v_cndmask_b32_e32 v156, 0, v158, vcc
	v_mul_f32_e32 v156, v156, v236
	v_cmp_eq_u32_e32 vcc, v222, v173
	v_mul_f32_e32 v157, v159, v156
	s_and_b64 vcc, s[38:39], vcc
	v_fma_f32 v156, v159, v156, v203
	v_cndmask_b32_e32 v159, v157, v156, vcc
	v_cvt_pk_bf16_f32 v156, v164, v165
	v_cvt_pk_bf16_f32 v157, v166, v167
	v_cvt_pk_bf16_f32 v158, v160, v161
	v_cvt_pk_bf16_f32 v159, v162, v159
	s_mov_b32 s94, s92
	s_mov_b32 s95, s92
	v_mfma_f32_16x16x32_bf16 v[136:139], v[136:139], v[156:159], v[144:147]
	v_or_b32_e32 v169, 64, v176
	s_mov_b32 s93, s92
	s_and_b64 vcc, exec, s[46:47]
	v_mfma_f32_16x16x32_bf16 v[144:147], v[148:151], v[156:159], v[152:155]
	v_exp_f32_e32 v148, v175
	v_add_u32_e32 v150, s5, v173
	v_ashrrev_i32_e32 v151, 31, v150
	v_lshlrev_b64 v[150:151], 13, v[150:151]
	v_pk_fma_f32 v[138:139], v[148:149], v[230:231], v[138:139] op_sel_hi:[0,1,1]
	v_pk_fma_f32 v[136:137], v[148:149], v[228:229], v[136:137] op_sel_hi:[0,1,1]
	v_lshl_add_u64 v[150:151], v[198:199], 0, v[150:151]
	v_cvt_pk_bf16_f32 v136, v136, v137
	v_cvt_pk_bf16_f32 v137, v138, v139
	global_store_dwordx2 v[150:151], v[136:137], off
	v_pk_fma_f32 v[136:137], v[148:149], v[226:227], v[146:147] op_sel_hi:[0,1,1]
	v_pk_fma_f32 v[138:139], v[148:149], v[224:225], v[144:145] op_sel_hi:[0,1,1]
	v_cvt_pk_bf16_f32 v138, v138, v139
	v_cvt_pk_bf16_f32 v139, v136, v137
	global_store_dwordx2 v[150:151], v[138:139], off offset:32
	global_load_dwordx4 v[136:139], v[200:201], off offset:192 nt
	v_mov_b64_e32 v[146:147], s[94:95]
	v_lshlrev_b32_e32 v152, 8, v169
	v_mov_b64_e32 v[150:151], s[94:95]
	v_mov_b64_e32 v[144:145], s[92:93]
	v_add_u32_e32 v156, s87, v152
	v_mov_b64_e32 v[148:149], s[92:93]
	s_cbranch_vccz .LBB0_532
	s_and_b64 vcc, exec, s[46:47]
	s_cbranch_vccz .LBB0_533

; #define VM_WAIT() asm volatile("s_waitcnt vmcnt(0)" ::: "memory")
;     __device__ __forceinline__ const char* b(const pg8::Unit& u) const { return (const char*)ws + boff + (size_t)u.pn * 256 * K_ * 2 + (u.kq < 0 ? 0 : u.kq * (K_ / 4) * 2); }
;     __device__ __forceinline__ const char* b(const pg8::Unit& u) const { return (const char*)ws + boff + (size_t)u.pn * 256 * D * 2; }
;     __device__ __forceinline__ const char* b(const pg8::Unit& u) const { return (const char*)ws + boff + (size_t)u.pn * 256 * D * 2; }
;     __device__ __forceinline__ const char* b(const pg8::Unit& u) const { return (const char*)ws + WS_A + ((size_t)u.pn * 256 * D + (size_t)(u.pm >> 1) * 256) * 2; }
; #define SCAN_DMA(dstbase, srcptr_row0, pitch_elems) do { _Pragma("unroll") for (int q_ = 0; q_ < 4; ++q_) { const int idx_ = tid + 512 * q_, row_ = idx_ >> 4, c16_ = (idx_ & 15) ^ (row_ & 15); \
;         __builtin_amdgcn_global_load_lds((const unsigned*)((srcptr_row0) + (size_t)row_ * (pitch_elems) + c16_ * 8), (LAS unsigned*)((dstbase) + (w * 64 + 512 * q_) * 16), 16, 0, 0); } } while (0)
; template <int MODE> __device__ __forceinline__ void ssd_scan_phase(Frame& F, int j, bool ctx_out) {
;     ...
;             VM_WAIT(); __syncthreads();
;             if (k + 1 < 18) {
;                 const int kn = k + 1; const bool isctxn = kn < 2; const int ccn = isctxn ? (dir == 0 ? kn : 1 - kn) : (dir == 0 ? kn - 2 : 17 - kn);
;                 const int row0n = isctxn ? MLAT + b * LCTX + ccn * 128 : b * LSEQ + ccn * 128;
;                 if ((ctx_out || !isctxn) && !(MODE & 8)) { SCAN_DMA(CS, cm + (size_t)row0n * GNW + g * 128, GNW); SCAN_DMA(GS, bm + (size_t)row0n * GNW + g * 128, GNW); }
;                 dtr0 = dtb[(size_t)(row0n + lane) * 128 + dir * 64 + h]; dtr1 = dtb[(size_t)(row0n + 64 + lane) * 128 + dir * 64 + h];
;             }
.Lscan_b4_y:
	s_add_i32 s40, s4, 1
	s_cmp_eq_u32 s4, 17
	s_mov_b32 s5, 17
	s_waitcnt lgkmcnt(0)
	s_barrier
	s_cbranch_scc1 .LBB0_481
	s_sub_i32 s17, 16, s4
	v_sub_co_u32_e64 v8, s[42:43], s4, 1
	s_and_b64 s[4:5], s[38:39], exec
	v_readfirstlane_b32 s4, v8
	s_cselect_b32 s4, s4, s17
	s_lshl_b32 s4, s4, 7
	s_add_i32 s17, s4, s81
	s_and_b64 s[4:5], s[42:43], exec
	s_cselect_b32 s4, s76, s17
	s_and_b64 s[42:43], s[28:29], s[42:43]
	s_and_b64 vcc, exec, s[42:43]
	s_cbranch_vccnz .LBB0_480
	s_ashr_i32 s5, s4, 31
	s_lshl_b64 s[42:43], s[4:5], 11
	v_ashrrev_i32_e32 v189, 31, v188
	s_add_u32 s44, s77, s42
	s_addc_u32 s45, s73, s43
	v_lshlrev_b64 v[8:9], 11, v[188:189]
	v_lshl_add_u64 v[10:11], s[44:45], 0, v[8:9]
	v_mov_b32_e32 v183, v177
	s_mov_b32 m0, s16
	v_ashrrev_i32_e32 v193, 31, v192
	v_lshl_add_u64 v[10:11], v[10:11], 0, v[182:183]
	global_load_lds_dwordx4 v[10:11], off nt
	v_lshlrev_b64 v[10:11], 11, v[192:193]
	v_lshl_add_u64 v[100:101], s[44:45], 0, v[10:11]
	v_mov_b32_e32 v185, v177
	v_ashrrev_i32_e32 v195, 31, v194
	v_lshl_add_u64 v[100:101], v[100:101], 0, v[184:185]
	s_add_i32 m0, s16, 0x2000
	v_mov_b32_e32 v187, v177
	global_load_lds_dwordx4 v[100:101], off nt
	v_lshlrev_b64 v[100:101], 11, v[194:195]
	v_lshl_add_u64 v[102:103], s[44:45], 0, v[100:101]
	v_lshl_add_u64 v[102:103], v[102:103], 0, v[186:187]
	s_add_i32 m0, s16, 0x4000
	v_ashrrev_i32_e32 v197, 31, v196
	global_load_lds_dwordx4 v[102:103], off nt
	s_add_i32 m0, s16, 0x6000
	v_lshlrev_b64 v[102:103], 11, v[196:197]
	s_add_u32 s42, s74, s42
	v_lshl_add_u64 v[104:105], s[44:45], 0, v[102:103]
	v_mov_b32_e32 v191, v177
	s_addc_u32 s43, s75, s43
	v_lshl_add_u64 v[104:105], v[104:105], 0, v[190:191]
	v_lshl_add_u64 v[8:9], s[42:43], 0, v[8:9]
	s_add_i32 s5, s87, s3
	global_load_lds_dwordx4 v[104:105], off nt
	v_lshl_add_u64 v[8:9], v[8:9], 0, v[182:183]
	s_mov_b32 m0, s5
	s_nop 0
	global_load_lds_dwordx4 v[8:9], off nt
	v_lshl_add_u64 v[8:9], s[42:43], 0, v[10:11]
	v_lshl_add_u64 v[8:9], v[8:9], 0, v[184:185]
	s_add_i32 m0, s5, 0x2000
	s_nop 0
	global_load_lds_dwordx4 v[8:9], off nt
	v_lshl_add_u64 v[8:9], s[42:43], 0, v[100:101]
	v_lshl_add_u64 v[8:9], v[8:9], 0, v[186:187]
	s_add_i32 m0, s5, 0x4000
	s_nop 0
	global_load_lds_dwordx4 v[8:9], off nt
	v_lshl_add_u64 v[8:9], s[42:43], 0, v[102:103]
	v_lshl_add_u64 v[8:9], v[8:9], 0, v[190:191]
	s_add_i32 m0, s5, 0x6000
	s_nop 0
	global_load_lds_dwordx4 v[8:9], off nt
	s_branch .LBB0_480
